# stack3 + M1 conv staging rewritten: hoisted weights/bias, batched row loads, same FMA order
# speedup vs baseline: 1.0074x; 1.0062x over previous
; DEVI int bid_() { int t = blockIdx.x; asm volatile("" : "+s"(t)); return t; }
; DEVI int gdim_() { int t = gridDim.x; asm volatile("" : "+s"(t)); return t; }
; DEVI unsigned pk2(float lo, float hi) { unsigned r; asm("v_cvt_pk_bf16_f32 %0, %1, %2" : "=v"(r) : "v"(lo), "v"(hi)); return r; }
; DEVI float bflo(unsigned w) { return __uint_as_float(w << 16); }
; DEVI float bfhi(unsigned w) { return __uint_as_float(w & 0xffff0000u); }
; DEVI void phase_m1(const Params& p, int l, unsigned char* smem) {
;     ...
;     for (int tile = bid_(); tile < NTILE; tile += gdim_()) {
;         const int row0 = tile * 128, nloc = tile % TPB;
;         for (int it = tid; it < 128 * 32; it += 512) {
;             const int t = it >> 5, c8 = (it & 31) * 8;
;             float a[8];
; #pragma unroll
;             for (int e = 0; e < 8; ++e) a[e] = p.in[15][l * 256 + c8 + e];
; #pragma unroll
;             for (int k = 0; k < 4; ++k) {
;                 const int tt = t - 3 + k;
;                 if (nloc * 128 + tt < 0) continue;
;                 const u32x4 x = *(const u32x4*)(proj + (size_t)(row0 + tt) * DIN + 1024 + c8);
;                 const f32x4 w0 = *(const f32x4*)(p.in[14] + ((size_t)l * 4 + k) * 256 + c8), w1 = *(const f32x4*)(p.in[14] + ((size_t)l * 4 + k) * 256 + c8 + 4);
;                 a[0] += w0[0] * bflo(x.x); a[1] += w0[1] * bfhi(x.x); a[2] += w0[2] * bflo(x.y); a[3] += w0[3] * bfhi(x.y);
;                 a[4] += w1[0] * bflo(x.z); a[5] += w1[1] * bfhi(x.z); a[6] += w1[2] * bflo(x.w); a[7] += w1[3] * bfhi(x.w);
;             }
;             u32x4 o; o.x = pk2(a[0], a[1]); o.y = pk2(a[2], a[3]); o.z = pk2(a[4], a[5]); o.w = pk2(a[6], a[7]);
;             *(u32x4*)(xc + t * 264 + c8) = o;
;         }
.LBB0_205:
	s_ashr_i32 s1, s0, 31
	s_lshr_b32 s14, s1, 25
	s_add_i32 s14, s0, s14
	s_and_b32 s14, s14, 0xffffff80
	s_lshl_b32 s38, s0, 7
	s_sub_i32 s28, s0, s14
	s_and_saveexec_b64 s[14:15], s[2:3]
	s_cbranch_execz .LBB0_216
	s_lshl_b32 s24, s28, 7
	s_sub_i32 s29, 0, s24
	s_add_i32 s39, s38, -1
	s_mov_b64 s[24:25], 0
	v_and_b32_e32 v174, 0xf8, v153
	v_lshlrev_b32_e32 v232, 1, v174
	v_mov_b32_e32 v233, 0
	v_lshlrev_b32_e32 v174, 2, v174
	global_load_dwordx4 v[0:3], v174, s[94:95]
	global_load_dwordx4 v[4:7], v174, s[94:95] offset:16
	global_load_dwordx4 v[8:11], v174, s[92:93]
	global_load_dwordx4 v[12:15], v174, s[92:93] offset:16
	global_load_dwordx4 v[16:19], v174, s[92:93] offset:1024
	global_load_dwordx4 v[20:23], v174, s[92:93] offset:1040
	global_load_dwordx4 v[176:179], v174, s[92:93] offset:2048
	global_load_dwordx4 v[180:183], v174, s[92:93] offset:2064
	global_load_dwordx4 v[184:187], v174, s[92:93] offset:3072
	global_load_dwordx4 v[188:191], v174, s[92:93] offset:3088
	v_ashrrev_i32_e32 v175, 5, v142
	v_add_u32_e32 v235, s38, v175
	v_add_u32_e32 v235, -3, v235
	v_mov_b64_e32 v[24:25], s[52:53]
	v_mad_i64_i32 v[24:25], s[40:41], v235, s35, v[24:25]
	v_lshl_add_u64 v[24:25], v[24:25], 0, v[232:233]
	s_mov_b64 s[98:99], 0x800
	v_lshl_add_u64 v[24:25], v[24:25], 0, s[98:99]
	s_mov_b64 s[98:99], 0x1800
	v_lshl_add_u64 v[26:27], v[24:25], 0, s[98:99]
	s_mov_b64 s[98:99], 0xc000
	v_mul_lo_u32 v234, v175, s34
	v_add3_u32 v234, s31, v234, v232
	global_load_dwordx4 v[192:195], v[24:25], off
	global_load_dwordx4 v[196:199], v[24:25], off offset:3072
	global_load_dwordx4 v[200:203], v[26:27], off
	global_load_dwordx4 v[204:207], v[26:27], off offset:3072
	v_lshl_add_u64 v[24:25], v[24:25], 0, s[98:99]
	v_lshl_add_u64 v[26:27], v[26:27], 0, s[98:99]
	global_load_dwordx4 v[208:211], v[24:25], off
	global_load_dwordx4 v[212:215], v[24:25], off offset:3072
	global_load_dwordx4 v[216:219], v[26:27], off
	global_load_dwordx4 v[220:223], v[26:27], off offset:3072
	v_lshl_add_u64 v[24:25], v[24:25], 0, s[98:99]
	v_lshl_add_u64 v[26:27], v[26:27], 0, s[98:99]
	s_waitcnt vmcnt(4)
	v_add_u32_e32 v28, -3, v175
	v_cmp_le_i32_e32 vcc, s29, v28
	s_nop 1
	v_cndmask_b32_e32 v192, 0, v192, vcc
	v_cndmask_b32_e32 v193, 0, v193, vcc
	v_cndmask_b32_e32 v194, 0, v194, vcc
	v_cndmask_b32_e32 v195, 0, v195, vcc
	v_add_u32_e32 v28, -2, v175
	v_cmp_le_i32_e32 vcc, s29, v28
	s_nop 1
	v_cndmask_b32_e32 v196, 0, v196, vcc
	v_cndmask_b32_e32 v197, 0, v197, vcc
	v_cndmask_b32_e32 v198, 0, v198, vcc
	v_cndmask_b32_e32 v199, 0, v199, vcc
	v_add_u32_e32 v28, -1, v175
	v_cmp_le_i32_e32 vcc, s29, v28
	s_nop 1
	v_cndmask_b32_e32 v200, 0, v200, vcc
	v_cndmask_b32_e32 v201, 0, v201, vcc
	v_cndmask_b32_e32 v202, 0, v202, vcc
	v_cndmask_b32_e32 v203, 0, v203, vcc
	v_mov_b64_e32 v[224:225], v[0:1]
	v_mov_b64_e32 v[226:227], v[2:3]
	v_mov_b64_e32 v[228:229], v[4:5]
	v_mov_b64_e32 v[230:231], v[6:7]
	v_lshlrev_b32_e32 v28, 16, v192
	v_and_b32_e32 v29, 0xffff0000, v192
	v_pk_fma_f32 v[224:225], v[8:9], v[28:29], v[224:225]
	v_lshlrev_b32_e32 v28, 16, v193
	v_and_b32_e32 v29, 0xffff0000, v193
	v_pk_fma_f32 v[226:227], v[10:11], v[28:29], v[226:227]
	v_lshlrev_b32_e32 v28, 16, v194
	v_and_b32_e32 v29, 0xffff0000, v194
	v_pk_fma_f32 v[228:229], v[12:13], v[28:29], v[228:229]
	v_lshlrev_b32_e32 v28, 16, v195
	v_and_b32_e32 v29, 0xffff0000, v195
	v_pk_fma_f32 v[230:231], v[14:15], v[28:29], v[230:231]
	v_lshlrev_b32_e32 v28, 16, v196
	v_and_b32_e32 v29, 0xffff0000, v196
	v_pk_fma_f32 v[224:225], v[16:17], v[28:29], v[224:225]
	v_lshlrev_b32_e32 v28, 16, v197
	v_and_b32_e32 v29, 0xffff0000, v197
	v_pk_fma_f32 v[226:227], v[18:19], v[28:29], v[226:227]
	v_lshlrev_b32_e32 v28, 16, v198
	v_and_b32_e32 v29, 0xffff0000, v198
	v_pk_fma_f32 v[228:229], v[20:21], v[28:29], v[228:229]
	v_lshlrev_b32_e32 v28, 16, v199
	v_and_b32_e32 v29, 0xffff0000, v199
	v_pk_fma_f32 v[230:231], v[22:23], v[28:29], v[230:231]
	v_lshlrev_b32_e32 v28, 16, v200
	v_and_b32_e32 v29, 0xffff0000, v200
	v_pk_fma_f32 v[224:225], v[176:177], v[28:29], v[224:225]
	v_lshlrev_b32_e32 v28, 16, v201
	v_and_b32_e32 v29, 0xffff0000, v201
	v_pk_fma_f32 v[226:227], v[178:179], v[28:29], v[226:227]
	v_lshlrev_b32_e32 v28, 16, v202
	v_and_b32_e32 v29, 0xffff0000, v202
	v_pk_fma_f32 v[228:229], v[180:181], v[28:29], v[228:229]
	v_lshlrev_b32_e32 v28, 16, v203
	v_and_b32_e32 v29, 0xffff0000, v203
	v_pk_fma_f32 v[230:231], v[182:183], v[28:29], v[230:231]
	v_lshlrev_b32_e32 v28, 16, v204
	v_and_b32_e32 v29, 0xffff0000, v204
	v_pk_fma_f32 v[224:225], v[184:185], v[28:29], v[224:225]
	v_lshlrev_b32_e32 v28, 16, v205
	v_and_b32_e32 v29, 0xffff0000, v205
	v_pk_fma_f32 v[226:227], v[186:187], v[28:29], v[226:227]
	v_lshlrev_b32_e32 v28, 16, v206
	v_and_b32_e32 v29, 0xffff0000, v206
	v_pk_fma_f32 v[228:229], v[188:189], v[28:29], v[228:229]
	v_lshlrev_b32_e32 v28, 16, v207
	v_and_b32_e32 v29, 0xffff0000, v207
	v_pk_fma_f32 v[230:231], v[190:191], v[28:29], v[230:231]
	v_cvt_pk_bf16_f32 v224, v224, v225
	v_cvt_pk_bf16_f32 v225, v226, v227
	v_cvt_pk_bf16_f32 v226, v228, v229
	v_cvt_pk_bf16_f32 v227, v230, v231
	ds_write_b128 v234, v[224:227]
	s_waitcnt vmcnt(0)
	s_waitcnt lgkmcnt(0)
; DEVI unsigned pk2(float lo, float hi) { unsigned r; asm("v_cvt_pk_bf16_f32 %0, %1, %2" : "=v"(r) : "v"(lo), "v"(hi)); return r; }
; DEVI float bflo(unsigned w) { return __uint_as_float(w << 16); }
; DEVI float bfhi(unsigned w) { return __uint_as_float(w & 0xffff0000u); }
; DEVI void phase_m1(const Params& p, int l, unsigned char* smem) {
;     ...
;         for (int it = tid; it < 128 * 32; it += 512) {
;             const int t = it >> 5, c8 = (it & 31) * 8;
;             float a[8];
; #pragma unroll
;             for (int e = 0; e < 8; ++e) a[e] = p.in[15][l * 256 + c8 + e];
; #pragma unroll
;             for (int k = 0; k < 4; ++k) {
;                 const int tt = t - 3 + k;
;                 if (nloc * 128 + tt < 0) continue;
;                 const u32x4 x = *(const u32x4*)(proj + (size_t)(row0 + tt) * DIN + 1024 + c8);
;                 const f32x4 w0 = *(const f32x4*)(p.in[14] + ((size_t)l * 4 + k) * 256 + c8), w1 = *(const f32x4*)(p.in[14] + ((size_t)l * 4 + k) * 256 + c8 + 4);
;                 a[0] += w0[0] * bflo(x.x); a[1] += w0[1] * bfhi(x.x); a[2] += w0[2] * bflo(x.y); a[3] += w0[3] * bfhi(x.y);
;                 a[4] += w1[0] * bflo(x.z); a[5] += w1[1] * bfhi(x.z); a[6] += w1[2] * bflo(x.w); a[7] += w1[3] * bfhi(x.w);
;             }
;             u32x4 o; o.x = pk2(a[0], a[1]); o.y = pk2(a[2], a[3]); o.z = pk2(a[4], a[5]); o.w = pk2(a[6], a[7]);
;             *(u32x4*)(xc + t * 264 + c8) = o;
;         }
	v_mov_b64_e32 v[224:225], v[0:1]
	v_mov_b64_e32 v[226:227], v[2:3]
	v_mov_b64_e32 v[228:229], v[4:5]
	v_mov_b64_e32 v[230:231], v[6:7]
	v_lshlrev_b32_e32 v28, 16, v208
	v_and_b32_e32 v29, 0xffff0000, v208
	v_pk_fma_f32 v[224:225], v[8:9], v[28:29], v[224:225]
	v_lshlrev_b32_e32 v28, 16, v209
	v_and_b32_e32 v29, 0xffff0000, v209
	v_pk_fma_f32 v[226:227], v[10:11], v[28:29], v[226:227]
	v_lshlrev_b32_e32 v28, 16, v210
	v_and_b32_e32 v29, 0xffff0000, v210
	v_pk_fma_f32 v[228:229], v[12:13], v[28:29], v[228:229]
	v_lshlrev_b32_e32 v28, 16, v211
	v_and_b32_e32 v29, 0xffff0000, v211
	v_pk_fma_f32 v[230:231], v[14:15], v[28:29], v[230:231]
	v_lshlrev_b32_e32 v28, 16, v212
	v_and_b32_e32 v29, 0xffff0000, v212
	v_pk_fma_f32 v[224:225], v[16:17], v[28:29], v[224:225]
	v_lshlrev_b32_e32 v28, 16, v213
	v_and_b32_e32 v29, 0xffff0000, v213
	v_pk_fma_f32 v[226:227], v[18:19], v[28:29], v[226:227]
	v_lshlrev_b32_e32 v28, 16, v214
	v_and_b32_e32 v29, 0xffff0000, v214
	v_pk_fma_f32 v[228:229], v[20:21], v[28:29], v[228:229]
	v_lshlrev_b32_e32 v28, 16, v215
	v_and_b32_e32 v29, 0xffff0000, v215
	v_pk_fma_f32 v[230:231], v[22:23], v[28:29], v[230:231]
	v_lshlrev_b32_e32 v28, 16, v216
	v_and_b32_e32 v29, 0xffff0000, v216
	v_pk_fma_f32 v[224:225], v[176:177], v[28:29], v[224:225]
	v_lshlrev_b32_e32 v28, 16, v217
	v_and_b32_e32 v29, 0xffff0000, v217
	v_pk_fma_f32 v[226:227], v[178:179], v[28:29], v[226:227]
	v_lshlrev_b32_e32 v28, 16, v218
	v_and_b32_e32 v29, 0xffff0000, v218
	v_pk_fma_f32 v[228:229], v[180:181], v[28:29], v[228:229]
	v_lshlrev_b32_e32 v28, 16, v219
	v_and_b32_e32 v29, 0xffff0000, v219
	v_pk_fma_f32 v[230:231], v[182:183], v[28:29], v[230:231]
	v_lshlrev_b32_e32 v28, 16, v220
	v_and_b32_e32 v29, 0xffff0000, v220
	v_pk_fma_f32 v[224:225], v[184:185], v[28:29], v[224:225]
	v_lshlrev_b32_e32 v28, 16, v221
	v_and_b32_e32 v29, 0xffff0000, v221
	v_pk_fma_f32 v[226:227], v[186:187], v[28:29], v[226:227]
	v_lshlrev_b32_e32 v28, 16, v222
	v_and_b32_e32 v29, 0xffff0000, v222
	v_pk_fma_f32 v[228:229], v[188:189], v[28:29], v[228:229]
	v_lshlrev_b32_e32 v28, 16, v223
	v_and_b32_e32 v29, 0xffff0000, v223
	v_pk_fma_f32 v[230:231], v[190:191], v[28:29], v[230:231]
	v_cvt_pk_bf16_f32 v224, v224, v225
	v_cvt_pk_bf16_f32 v225, v226, v227
	v_cvt_pk_bf16_f32 v226, v228, v229
	v_cvt_pk_bf16_f32 v227, v230, v231
	ds_write_b128 v234, v[224:227] offset:8448
	global_load_dwordx4 v[192:195], v[24:25], off
	global_load_dwordx4 v[196:199], v[24:25], off offset:3072
	global_load_dwordx4 v[200:203], v[26:27], off
	global_load_dwordx4 v[204:207], v[26:27], off offset:3072
	v_lshl_add_u64 v[24:25], v[24:25], 0, s[98:99]
	v_lshl_add_u64 v[26:27], v[26:27], 0, s[98:99]
	global_load_dwordx4 v[208:211], v[24:25], off
	global_load_dwordx4 v[212:215], v[24:25], off offset:3072
	global_load_dwordx4 v[216:219], v[26:27], off
	global_load_dwordx4 v[220:223], v[26:27], off offset:3072
	v_lshl_add_u64 v[24:25], v[24:25], 0, s[98:99]
	v_lshl_add_u64 v[26:27], v[26:27], 0, s[98:99]
	s_waitcnt vmcnt(4)
	s_waitcnt lgkmcnt(0)
	v_mov_b64_e32 v[224:225], v[0:1]
	v_mov_b64_e32 v[226:227], v[2:3]
	v_mov_b64_e32 v[228:229], v[4:5]
	v_mov_b64_e32 v[230:231], v[6:7]
	v_lshlrev_b32_e32 v28, 16, v192
	v_and_b32_e32 v29, 0xffff0000, v192
	v_pk_fma_f32 v[224:225], v[8:9], v[28:29], v[224:225]
	v_lshlrev_b32_e32 v28, 16, v193
	v_and_b32_e32 v29, 0xffff0000, v193
	v_pk_fma_f32 v[226:227], v[10:11], v[28:29], v[226:227]
	v_lshlrev_b32_e32 v28, 16, v194
	v_and_b32_e32 v29, 0xffff0000, v194
	v_pk_fma_f32 v[228:229], v[12:13], v[28:29], v[228:229]
	v_lshlrev_b32_e32 v28, 16, v195
	v_and_b32_e32 v29, 0xffff0000, v195
	v_pk_fma_f32 v[230:231], v[14:15], v[28:29], v[230:231]
	v_lshlrev_b32_e32 v28, 16, v196
	v_and_b32_e32 v29, 0xffff0000, v196
	v_pk_fma_f32 v[224:225], v[16:17], v[28:29], v[224:225]
	v_lshlrev_b32_e32 v28, 16, v197
	v_and_b32_e32 v29, 0xffff0000, v197
	v_pk_fma_f32 v[226:227], v[18:19], v[28:29], v[226:227]
	v_lshlrev_b32_e32 v28, 16, v198
	v_and_b32_e32 v29, 0xffff0000, v198
	v_pk_fma_f32 v[228:229], v[20:21], v[28:29], v[228:229]
	v_lshlrev_b32_e32 v28, 16, v199
	v_and_b32_e32 v29, 0xffff0000, v199
	v_pk_fma_f32 v[230:231], v[22:23], v[28:29], v[230:231]
	v_lshlrev_b32_e32 v28, 16, v200
	v_and_b32_e32 v29, 0xffff0000, v200
	v_pk_fma_f32 v[224:225], v[176:177], v[28:29], v[224:225]
	v_lshlrev_b32_e32 v28, 16, v201
	v_and_b32_e32 v29, 0xffff0000, v201
	v_pk_fma_f32 v[226:227], v[178:179], v[28:29], v[226:227]
	v_lshlrev_b32_e32 v28, 16, v202
	v_and_b32_e32 v29, 0xffff0000, v202
	v_pk_fma_f32 v[228:229], v[180:181], v[28:29], v[228:229]
	v_lshlrev_b32_e32 v28, 16, v203
	v_and_b32_e32 v29, 0xffff0000, v203
	v_pk_fma_f32 v[230:231], v[182:183], v[28:29], v[230:231]
	v_lshlrev_b32_e32 v28, 16, v204
	v_and_b32_e32 v29, 0xffff0000, v204
	v_pk_fma_f32 v[224:225], v[184:185], v[28:29], v[224:225]
	v_lshlrev_b32_e32 v28, 16, v205
	v_and_b32_e32 v29, 0xffff0000, v205
	v_pk_fma_f32 v[226:227], v[186:187], v[28:29], v[226:227]
	v_lshlrev_b32_e32 v28, 16, v206
	v_and_b32_e32 v29, 0xffff0000, v206
	v_pk_fma_f32 v[228:229], v[188:189], v[28:29], v[228:229]
	v_lshlrev_b32_e32 v28, 16, v207
	v_and_b32_e32 v29, 0xffff0000, v207
	v_pk_fma_f32 v[230:231], v[190:191], v[28:29], v[230:231]
	v_cvt_pk_bf16_f32 v224, v224, v225
	v_cvt_pk_bf16_f32 v225, v226, v227
	v_cvt_pk_bf16_f32 v226, v228, v229
	v_cvt_pk_bf16_f32 v227, v230, v231
	ds_write_b128 v234, v[224:227] offset:16896
	s_waitcnt vmcnt(0)
	s_waitcnt lgkmcnt(0)
; DEVI unsigned pk2(float lo, float hi) { unsigned r; asm("v_cvt_pk_bf16_f32 %0, %1, %2" : "=v"(r) : "v"(lo), "v"(hi)); return r; }
; DEVI float bflo(unsigned w) { return __uint_as_float(w << 16); }
; DEVI float bfhi(unsigned w) { return __uint_as_float(w & 0xffff0000u); }
; DEVI void phase_m1(const Params& p, int l, unsigned char* smem) {
;     ...
;         for (int it = tid; it < 128 * 32; it += 512) {
;             const int t = it >> 5, c8 = (it & 31) * 8;
;             float a[8];
; #pragma unroll
;             for (int e = 0; e < 8; ++e) a[e] = p.in[15][l * 256 + c8 + e];
; #pragma unroll
;             for (int k = 0; k < 4; ++k) {
;                 const int tt = t - 3 + k;
;                 if (nloc * 128 + tt < 0) continue;
;                 const u32x4 x = *(const u32x4*)(proj + (size_t)(row0 + tt) * DIN + 1024 + c8);
;                 const f32x4 w0 = *(const f32x4*)(p.in[14] + ((size_t)l * 4 + k) * 256 + c8), w1 = *(const f32x4*)(p.in[14] + ((size_t)l * 4 + k) * 256 + c8 + 4);
;                 a[0] += w0[0] * bflo(x.x); a[1] += w0[1] * bfhi(x.x); a[2] += w0[2] * bflo(x.y); a[3] += w0[3] * bfhi(x.y);
;                 a[4] += w1[0] * bflo(x.z); a[5] += w1[1] * bfhi(x.z); a[6] += w1[2] * bflo(x.w); a[7] += w1[3] * bfhi(x.w);
;             }
;             u32x4 o; o.x = pk2(a[0], a[1]); o.y = pk2(a[2], a[3]); o.z = pk2(a[4], a[5]); o.w = pk2(a[6], a[7]);
;             *(u32x4*)(xc + t * 264 + c8) = o;
;         }
	v_mov_b64_e32 v[224:225], v[0:1]
	v_mov_b64_e32 v[226:227], v[2:3]
	v_mov_b64_e32 v[228:229], v[4:5]
	v_mov_b64_e32 v[230:231], v[6:7]
	v_lshlrev_b32_e32 v28, 16, v208
	v_and_b32_e32 v29, 0xffff0000, v208
	v_pk_fma_f32 v[224:225], v[8:9], v[28:29], v[224:225]
	v_lshlrev_b32_e32 v28, 16, v209
	v_and_b32_e32 v29, 0xffff0000, v209
	v_pk_fma_f32 v[226:227], v[10:11], v[28:29], v[226:227]
	v_lshlrev_b32_e32 v28, 16, v210
	v_and_b32_e32 v29, 0xffff0000, v210
	v_pk_fma_f32 v[228:229], v[12:13], v[28:29], v[228:229]
	v_lshlrev_b32_e32 v28, 16, v211
	v_and_b32_e32 v29, 0xffff0000, v211
	v_pk_fma_f32 v[230:231], v[14:15], v[28:29], v[230:231]
	v_lshlrev_b32_e32 v28, 16, v212
	v_and_b32_e32 v29, 0xffff0000, v212
	v_pk_fma_f32 v[224:225], v[16:17], v[28:29], v[224:225]
	v_lshlrev_b32_e32 v28, 16, v213
	v_and_b32_e32 v29, 0xffff0000, v213
	v_pk_fma_f32 v[226:227], v[18:19], v[28:29], v[226:227]
	v_lshlrev_b32_e32 v28, 16, v214
	v_and_b32_e32 v29, 0xffff0000, v214
	v_pk_fma_f32 v[228:229], v[20:21], v[28:29], v[228:229]
	v_lshlrev_b32_e32 v28, 16, v215
	v_and_b32_e32 v29, 0xffff0000, v215
	v_pk_fma_f32 v[230:231], v[22:23], v[28:29], v[230:231]
	v_lshlrev_b32_e32 v28, 16, v216
	v_and_b32_e32 v29, 0xffff0000, v216
	v_pk_fma_f32 v[224:225], v[176:177], v[28:29], v[224:225]
	v_lshlrev_b32_e32 v28, 16, v217
	v_and_b32_e32 v29, 0xffff0000, v217
	v_pk_fma_f32 v[226:227], v[178:179], v[28:29], v[226:227]
	v_lshlrev_b32_e32 v28, 16, v218
	v_and_b32_e32 v29, 0xffff0000, v218
	v_pk_fma_f32 v[228:229], v[180:181], v[28:29], v[228:229]
	v_lshlrev_b32_e32 v28, 16, v219
	v_and_b32_e32 v29, 0xffff0000, v219
	v_pk_fma_f32 v[230:231], v[182:183], v[28:29], v[230:231]
	v_lshlrev_b32_e32 v28, 16, v220
	v_and_b32_e32 v29, 0xffff0000, v220
	v_pk_fma_f32 v[224:225], v[184:185], v[28:29], v[224:225]
	v_lshlrev_b32_e32 v28, 16, v221
	v_and_b32_e32 v29, 0xffff0000, v221
	v_pk_fma_f32 v[226:227], v[186:187], v[28:29], v[226:227]
	v_lshlrev_b32_e32 v28, 16, v222
	v_and_b32_e32 v29, 0xffff0000, v222
	v_pk_fma_f32 v[228:229], v[188:189], v[28:29], v[228:229]
	v_lshlrev_b32_e32 v28, 16, v223
	v_and_b32_e32 v29, 0xffff0000, v223
	v_pk_fma_f32 v[230:231], v[190:191], v[28:29], v[230:231]
	v_cvt_pk_bf16_f32 v224, v224, v225
	v_cvt_pk_bf16_f32 v225, v226, v227
	v_cvt_pk_bf16_f32 v226, v228, v229
	v_cvt_pk_bf16_f32 v227, v230, v231
	ds_write_b128 v234, v[224:227] offset:25344
	global_load_dwordx4 v[192:195], v[24:25], off
	global_load_dwordx4 v[196:199], v[24:25], off offset:3072
	global_load_dwordx4 v[200:203], v[26:27], off
	global_load_dwordx4 v[204:207], v[26:27], off offset:3072
	v_lshl_add_u64 v[24:25], v[24:25], 0, s[98:99]
	v_lshl_add_u64 v[26:27], v[26:27], 0, s[98:99]
	global_load_dwordx4 v[208:211], v[24:25], off
	global_load_dwordx4 v[212:215], v[24:25], off offset:3072
	global_load_dwordx4 v[216:219], v[26:27], off
	global_load_dwordx4 v[220:223], v[26:27], off offset:3072
	v_lshl_add_u64 v[24:25], v[24:25], 0, s[98:99]
	v_lshl_add_u64 v[26:27], v[26:27], 0, s[98:99]
	s_waitcnt vmcnt(4)
	s_waitcnt lgkmcnt(0)
	v_mov_b64_e32 v[224:225], v[0:1]
	v_mov_b64_e32 v[226:227], v[2:3]
	v_mov_b64_e32 v[228:229], v[4:5]
	v_mov_b64_e32 v[230:231], v[6:7]
	v_lshlrev_b32_e32 v28, 16, v192
	v_and_b32_e32 v29, 0xffff0000, v192
	v_pk_fma_f32 v[224:225], v[8:9], v[28:29], v[224:225]
	v_lshlrev_b32_e32 v28, 16, v193
	v_and_b32_e32 v29, 0xffff0000, v193
	v_pk_fma_f32 v[226:227], v[10:11], v[28:29], v[226:227]
	v_lshlrev_b32_e32 v28, 16, v194
	v_and_b32_e32 v29, 0xffff0000, v194
	v_pk_fma_f32 v[228:229], v[12:13], v[28:29], v[228:229]
	v_lshlrev_b32_e32 v28, 16, v195
	v_and_b32_e32 v29, 0xffff0000, v195
	v_pk_fma_f32 v[230:231], v[14:15], v[28:29], v[230:231]
	v_lshlrev_b32_e32 v28, 16, v196
	v_and_b32_e32 v29, 0xffff0000, v196
	v_pk_fma_f32 v[224:225], v[16:17], v[28:29], v[224:225]
	v_lshlrev_b32_e32 v28, 16, v197
	v_and_b32_e32 v29, 0xffff0000, v197
	v_pk_fma_f32 v[226:227], v[18:19], v[28:29], v[226:227]
	v_lshlrev_b32_e32 v28, 16, v198
	v_and_b32_e32 v29, 0xffff0000, v198
	v_pk_fma_f32 v[228:229], v[20:21], v[28:29], v[228:229]
	v_lshlrev_b32_e32 v28, 16, v199
	v_and_b32_e32 v29, 0xffff0000, v199
	v_pk_fma_f32 v[230:231], v[22:23], v[28:29], v[230:231]
	v_lshlrev_b32_e32 v28, 16, v200
	v_and_b32_e32 v29, 0xffff0000, v200
	v_pk_fma_f32 v[224:225], v[176:177], v[28:29], v[224:225]
	v_lshlrev_b32_e32 v28, 16, v201
	v_and_b32_e32 v29, 0xffff0000, v201
	v_pk_fma_f32 v[226:227], v[178:179], v[28:29], v[226:227]
	v_lshlrev_b32_e32 v28, 16, v202
	v_and_b32_e32 v29, 0xffff0000, v202
	v_pk_fma_f32 v[228:229], v[180:181], v[28:29], v[228:229]
	v_lshlrev_b32_e32 v28, 16, v203
	v_and_b32_e32 v29, 0xffff0000, v203
	v_pk_fma_f32 v[230:231], v[182:183], v[28:29], v[230:231]
	v_lshlrev_b32_e32 v28, 16, v204
	v_and_b32_e32 v29, 0xffff0000, v204
	v_pk_fma_f32 v[224:225], v[184:185], v[28:29], v[224:225]
	v_lshlrev_b32_e32 v28, 16, v205
	v_and_b32_e32 v29, 0xffff0000, v205
	v_pk_fma_f32 v[226:227], v[186:187], v[28:29], v[226:227]
	v_lshlrev_b32_e32 v28, 16, v206
	v_and_b32_e32 v29, 0xffff0000, v206
	v_pk_fma_f32 v[228:229], v[188:189], v[28:29], v[228:229]
	v_lshlrev_b32_e32 v28, 16, v207
	v_and_b32_e32 v29, 0xffff0000, v207
	v_pk_fma_f32 v[230:231], v[190:191], v[28:29], v[230:231]
	v_cvt_pk_bf16_f32 v224, v224, v225
	v_cvt_pk_bf16_f32 v225, v226, v227
	v_cvt_pk_bf16_f32 v226, v228, v229
	v_cvt_pk_bf16_f32 v227, v230, v231
	ds_write_b128 v234, v[224:227] offset:33792
	s_waitcnt vmcnt(0)
	s_waitcnt lgkmcnt(0)
; DEVI unsigned pk2(float lo, float hi) { unsigned r; asm("v_cvt_pk_bf16_f32 %0, %1, %2" : "=v"(r) : "v"(lo), "v"(hi)); return r; }
; DEVI float bflo(unsigned w) { return __uint_as_float(w << 16); }
; DEVI float bfhi(unsigned w) { return __uint_as_float(w & 0xffff0000u); }
; DEVI void phase_m1(const Params& p, int l, unsigned char* smem) {
;     ...
;         for (int it = tid; it < 128 * 32; it += 512) {
;             const int t = it >> 5, c8 = (it & 31) * 8;
;             float a[8];
; #pragma unroll
;             for (int e = 0; e < 8; ++e) a[e] = p.in[15][l * 256 + c8 + e];
; #pragma unroll
;             for (int k = 0; k < 4; ++k) {
;                 const int tt = t - 3 + k;
;                 if (nloc * 128 + tt < 0) continue;
;                 const u32x4 x = *(const u32x4*)(proj + (size_t)(row0 + tt) * DIN + 1024 + c8);
;                 const f32x4 w0 = *(const f32x4*)(p.in[14] + ((size_t)l * 4 + k) * 256 + c8), w1 = *(const f32x4*)(p.in[14] + ((size_t)l * 4 + k) * 256 + c8 + 4);
;                 a[0] += w0[0] * bflo(x.x); a[1] += w0[1] * bfhi(x.x); a[2] += w0[2] * bflo(x.y); a[3] += w0[3] * bfhi(x.y);
;                 a[4] += w1[0] * bflo(x.z); a[5] += w1[1] * bfhi(x.z); a[6] += w1[2] * bflo(x.w); a[7] += w1[3] * bfhi(x.w);
;             }
;             u32x4 o; o.x = pk2(a[0], a[1]); o.y = pk2(a[2], a[3]); o.z = pk2(a[4], a[5]); o.w = pk2(a[6], a[7]);
;             *(u32x4*)(xc + t * 264 + c8) = o;
;         }
	v_mov_b64_e32 v[224:225], v[0:1]
	v_mov_b64_e32 v[226:227], v[2:3]
	v_mov_b64_e32 v[228:229], v[4:5]
	v_mov_b64_e32 v[230:231], v[6:7]
	v_lshlrev_b32_e32 v28, 16, v208
	v_and_b32_e32 v29, 0xffff0000, v208
	v_pk_fma_f32 v[224:225], v[8:9], v[28:29], v[224:225]
	v_lshlrev_b32_e32 v28, 16, v209
	v_and_b32_e32 v29, 0xffff0000, v209
	v_pk_fma_f32 v[226:227], v[10:11], v[28:29], v[226:227]
	v_lshlrev_b32_e32 v28, 16, v210
	v_and_b32_e32 v29, 0xffff0000, v210
	v_pk_fma_f32 v[228:229], v[12:13], v[28:29], v[228:229]
	v_lshlrev_b32_e32 v28, 16, v211
	v_and_b32_e32 v29, 0xffff0000, v211
	v_pk_fma_f32 v[230:231], v[14:15], v[28:29], v[230:231]
	v_lshlrev_b32_e32 v28, 16, v212
	v_and_b32_e32 v29, 0xffff0000, v212
	v_pk_fma_f32 v[224:225], v[16:17], v[28:29], v[224:225]
	v_lshlrev_b32_e32 v28, 16, v213
	v_and_b32_e32 v29, 0xffff0000, v213
	v_pk_fma_f32 v[226:227], v[18:19], v[28:29], v[226:227]
	v_lshlrev_b32_e32 v28, 16, v214
	v_and_b32_e32 v29, 0xffff0000, v214
	v_pk_fma_f32 v[228:229], v[20:21], v[28:29], v[228:229]
	v_lshlrev_b32_e32 v28, 16, v215
	v_and_b32_e32 v29, 0xffff0000, v215
	v_pk_fma_f32 v[230:231], v[22:23], v[28:29], v[230:231]
	v_lshlrev_b32_e32 v28, 16, v216
	v_and_b32_e32 v29, 0xffff0000, v216
	v_pk_fma_f32 v[224:225], v[176:177], v[28:29], v[224:225]
	v_lshlrev_b32_e32 v28, 16, v217
	v_and_b32_e32 v29, 0xffff0000, v217
	v_pk_fma_f32 v[226:227], v[178:179], v[28:29], v[226:227]
	v_lshlrev_b32_e32 v28, 16, v218
	v_and_b32_e32 v29, 0xffff0000, v218
	v_pk_fma_f32 v[228:229], v[180:181], v[28:29], v[228:229]
	v_lshlrev_b32_e32 v28, 16, v219
	v_and_b32_e32 v29, 0xffff0000, v219
	v_pk_fma_f32 v[230:231], v[182:183], v[28:29], v[230:231]
	v_lshlrev_b32_e32 v28, 16, v220
	v_and_b32_e32 v29, 0xffff0000, v220
	v_pk_fma_f32 v[224:225], v[184:185], v[28:29], v[224:225]
	v_lshlrev_b32_e32 v28, 16, v221
	v_and_b32_e32 v29, 0xffff0000, v221
	v_pk_fma_f32 v[226:227], v[186:187], v[28:29], v[226:227]
	v_lshlrev_b32_e32 v28, 16, v222
	v_and_b32_e32 v29, 0xffff0000, v222
	v_pk_fma_f32 v[228:229], v[188:189], v[28:29], v[228:229]
	v_lshlrev_b32_e32 v28, 16, v223
	v_and_b32_e32 v29, 0xffff0000, v223
	v_pk_fma_f32 v[230:231], v[190:191], v[28:29], v[230:231]
	v_cvt_pk_bf16_f32 v224, v224, v225
	v_cvt_pk_bf16_f32 v225, v226, v227
	v_cvt_pk_bf16_f32 v226, v228, v229
	v_cvt_pk_bf16_f32 v227, v230, v231
	ds_write_b128 v234, v[224:227] offset:42240
	global_load_dwordx4 v[192:195], v[24:25], off
	global_load_dwordx4 v[196:199], v[24:25], off offset:3072
	global_load_dwordx4 v[200:203], v[26:27], off
	global_load_dwordx4 v[204:207], v[26:27], off offset:3072
	v_lshl_add_u64 v[24:25], v[24:25], 0, s[98:99]
	v_lshl_add_u64 v[26:27], v[26:27], 0, s[98:99]
	global_load_dwordx4 v[208:211], v[24:25], off
	global_load_dwordx4 v[212:215], v[24:25], off offset:3072
	global_load_dwordx4 v[216:219], v[26:27], off
	global_load_dwordx4 v[220:223], v[26:27], off offset:3072
	v_lshl_add_u64 v[24:25], v[24:25], 0, s[98:99]
	v_lshl_add_u64 v[26:27], v[26:27], 0, s[98:99]
	s_waitcnt vmcnt(4)
	s_waitcnt lgkmcnt(0)
; DEVI unsigned pk2(float lo, float hi) { unsigned r; asm("v_cvt_pk_bf16_f32 %0, %1, %2" : "=v"(r) : "v"(lo), "v"(hi)); return r; }
; DEVI float bflo(unsigned w) { return __uint_as_float(w << 16); }
; DEVI float bfhi(unsigned w) { return __uint_as_float(w & 0xffff0000u); }
; DEVI void phase_m1(const Params& p, int l, unsigned char* smem) {
;     ...
;         for (int it = tid; it < 128 * 32; it += 512) {
;             const int t = it >> 5, c8 = (it & 31) * 8;
;             float a[8];
; #pragma unroll
;             for (int e = 0; e < 8; ++e) a[e] = p.in[15][l * 256 + c8 + e];
; #pragma unroll
;             for (int k = 0; k < 4; ++k) {
;                 const int tt = t - 3 + k;
;                 if (nloc * 128 + tt < 0) continue;
;                 const u32x4 x = *(const u32x4*)(proj + (size_t)(row0 + tt) * DIN + 1024 + c8);
;                 const f32x4 w0 = *(const f32x4*)(p.in[14] + ((size_t)l * 4 + k) * 256 + c8), w1 = *(const f32x4*)(p.in[14] + ((size_t)l * 4 + k) * 256 + c8 + 4);
;                 a[0] += w0[0] * bflo(x.x); a[1] += w0[1] * bfhi(x.x); a[2] += w0[2] * bflo(x.y); a[3] += w0[3] * bfhi(x.y);
;                 a[4] += w1[0] * bflo(x.z); a[5] += w1[1] * bfhi(x.z); a[6] += w1[2] * bflo(x.w); a[7] += w1[3] * bfhi(x.w);
;             }
;             u32x4 o; o.x = pk2(a[0], a[1]); o.y = pk2(a[2], a[3]); o.z = pk2(a[4], a[5]); o.w = pk2(a[6], a[7]);
;             *(u32x4*)(xc + t * 264 + c8) = o;
;         }
	v_mov_b64_e32 v[224:225], v[0:1]
	v_mov_b64_e32 v[226:227], v[2:3]
	v_mov_b64_e32 v[228:229], v[4:5]
	v_mov_b64_e32 v[230:231], v[6:7]
	v_lshlrev_b32_e32 v28, 16, v192
	v_and_b32_e32 v29, 0xffff0000, v192
	v_pk_fma_f32 v[224:225], v[8:9], v[28:29], v[224:225]
	v_lshlrev_b32_e32 v28, 16, v193
	v_and_b32_e32 v29, 0xffff0000, v193
	v_pk_fma_f32 v[226:227], v[10:11], v[28:29], v[226:227]
	v_lshlrev_b32_e32 v28, 16, v194
	v_and_b32_e32 v29, 0xffff0000, v194
	v_pk_fma_f32 v[228:229], v[12:13], v[28:29], v[228:229]
	v_lshlrev_b32_e32 v28, 16, v195
	v_and_b32_e32 v29, 0xffff0000, v195
	v_pk_fma_f32 v[230:231], v[14:15], v[28:29], v[230:231]
	v_lshlrev_b32_e32 v28, 16, v196
	v_and_b32_e32 v29, 0xffff0000, v196
	v_pk_fma_f32 v[224:225], v[16:17], v[28:29], v[224:225]
	v_lshlrev_b32_e32 v28, 16, v197
	v_and_b32_e32 v29, 0xffff0000, v197
	v_pk_fma_f32 v[226:227], v[18:19], v[28:29], v[226:227]
	v_lshlrev_b32_e32 v28, 16, v198
	v_and_b32_e32 v29, 0xffff0000, v198
	v_pk_fma_f32 v[228:229], v[20:21], v[28:29], v[228:229]
	v_lshlrev_b32_e32 v28, 16, v199
	v_and_b32_e32 v29, 0xffff0000, v199
	v_pk_fma_f32 v[230:231], v[22:23], v[28:29], v[230:231]
	v_lshlrev_b32_e32 v28, 16, v200
	v_and_b32_e32 v29, 0xffff0000, v200
	v_pk_fma_f32 v[224:225], v[176:177], v[28:29], v[224:225]
	v_lshlrev_b32_e32 v28, 16, v201
	v_and_b32_e32 v29, 0xffff0000, v201
	v_pk_fma_f32 v[226:227], v[178:179], v[28:29], v[226:227]
	v_lshlrev_b32_e32 v28, 16, v202
	v_and_b32_e32 v29, 0xffff0000, v202
	v_pk_fma_f32 v[228:229], v[180:181], v[28:29], v[228:229]
	v_lshlrev_b32_e32 v28, 16, v203
	v_and_b32_e32 v29, 0xffff0000, v203
	v_pk_fma_f32 v[230:231], v[182:183], v[28:29], v[230:231]
	v_lshlrev_b32_e32 v28, 16, v204
	v_and_b32_e32 v29, 0xffff0000, v204
	v_pk_fma_f32 v[224:225], v[184:185], v[28:29], v[224:225]
	v_lshlrev_b32_e32 v28, 16, v205
	v_and_b32_e32 v29, 0xffff0000, v205
	v_pk_fma_f32 v[226:227], v[186:187], v[28:29], v[226:227]
	v_lshlrev_b32_e32 v28, 16, v206
	v_and_b32_e32 v29, 0xffff0000, v206
	v_pk_fma_f32 v[228:229], v[188:189], v[28:29], v[228:229]
	v_lshlrev_b32_e32 v28, 16, v207
	v_and_b32_e32 v29, 0xffff0000, v207
	v_pk_fma_f32 v[230:231], v[190:191], v[28:29], v[230:231]
	v_cvt_pk_bf16_f32 v224, v224, v225
	v_cvt_pk_bf16_f32 v225, v226, v227
	v_cvt_pk_bf16_f32 v226, v228, v229
	v_cvt_pk_bf16_f32 v227, v230, v231
	ds_write_b128 v234, v[224:227] offset:50688
	s_waitcnt vmcnt(0)
	s_waitcnt lgkmcnt(0)
	v_mov_b64_e32 v[224:225], v[0:1]
	v_mov_b64_e32 v[226:227], v[2:3]
	v_mov_b64_e32 v[228:229], v[4:5]
	v_mov_b64_e32 v[230:231], v[6:7]
	v_lshlrev_b32_e32 v28, 16, v208
	v_and_b32_e32 v29, 0xffff0000, v208
	v_pk_fma_f32 v[224:225], v[8:9], v[28:29], v[224:225]
	v_lshlrev_b32_e32 v28, 16, v209
	v_and_b32_e32 v29, 0xffff0000, v209
	v_pk_fma_f32 v[226:227], v[10:11], v[28:29], v[226:227]
	v_lshlrev_b32_e32 v28, 16, v210
	v_and_b32_e32 v29, 0xffff0000, v210
	v_pk_fma_f32 v[228:229], v[12:13], v[28:29], v[228:229]
	v_lshlrev_b32_e32 v28, 16, v211
	v_and_b32_e32 v29, 0xffff0000, v211
	v_pk_fma_f32 v[230:231], v[14:15], v[28:29], v[230:231]
	v_lshlrev_b32_e32 v28, 16, v212
	v_and_b32_e32 v29, 0xffff0000, v212
	v_pk_fma_f32 v[224:225], v[16:17], v[28:29], v[224:225]
	v_lshlrev_b32_e32 v28, 16, v213
	v_and_b32_e32 v29, 0xffff0000, v213
	v_pk_fma_f32 v[226:227], v[18:19], v[28:29], v[226:227]
	v_lshlrev_b32_e32 v28, 16, v214
	v_and_b32_e32 v29, 0xffff0000, v214
	v_pk_fma_f32 v[228:229], v[20:21], v[28:29], v[228:229]
	v_lshlrev_b32_e32 v28, 16, v215
	v_and_b32_e32 v29, 0xffff0000, v215
	v_pk_fma_f32 v[230:231], v[22:23], v[28:29], v[230:231]
	v_lshlrev_b32_e32 v28, 16, v216
	v_and_b32_e32 v29, 0xffff0000, v216
	v_pk_fma_f32 v[224:225], v[176:177], v[28:29], v[224:225]
	v_lshlrev_b32_e32 v28, 16, v217
	v_and_b32_e32 v29, 0xffff0000, v217
	v_pk_fma_f32 v[226:227], v[178:179], v[28:29], v[226:227]
	v_lshlrev_b32_e32 v28, 16, v218
	v_and_b32_e32 v29, 0xffff0000, v218
	v_pk_fma_f32 v[228:229], v[180:181], v[28:29], v[228:229]
	v_lshlrev_b32_e32 v28, 16, v219
	v_and_b32_e32 v29, 0xffff0000, v219
	v_pk_fma_f32 v[230:231], v[182:183], v[28:29], v[230:231]
	v_lshlrev_b32_e32 v28, 16, v220
	v_and_b32_e32 v29, 0xffff0000, v220
	v_pk_fma_f32 v[224:225], v[184:185], v[28:29], v[224:225]
	v_lshlrev_b32_e32 v28, 16, v221
	v_and_b32_e32 v29, 0xffff0000, v221
	v_pk_fma_f32 v[226:227], v[186:187], v[28:29], v[226:227]
	v_lshlrev_b32_e32 v28, 16, v222
	v_and_b32_e32 v29, 0xffff0000, v222
	v_pk_fma_f32 v[228:229], v[188:189], v[28:29], v[228:229]
	v_lshlrev_b32_e32 v28, 16, v223
	v_and_b32_e32 v29, 0xffff0000, v223
	v_pk_fma_f32 v[230:231], v[190:191], v[28:29], v[230:231]
	v_cvt_pk_bf16_f32 v224, v224, v225
	v_cvt_pk_bf16_f32 v225, v226, v227
	v_cvt_pk_bf16_f32 v226, v228, v229
	v_cvt_pk_bf16_f32 v227, v230, v231
	ds_write_b128 v234, v[224:227] offset:59136

; DEVI int bid_() { int t = blockIdx.x; asm volatile("" : "+s"(t)); return t; }
; DEVI int gdim_() { int t = gridDim.x; asm volatile("" : "+s"(t)); return t; }
; DEVI unsigned pk2(float lo, float hi) { unsigned r; asm("v_cvt_pk_bf16_f32 %0, %1, %2" : "=v"(r) : "v"(lo), "v"(hi)); return r; }
; DEVI float bflo(unsigned w) { return __uint_as_float(w << 16); }
; DEVI float bfhi(unsigned w) { return __uint_as_float(w & 0xffff0000u); }
; DEVI void phase_m1(const Params& p, int l, unsigned char* smem) {
;     ...
;     for (int tile = bid_(); tile < NTILE; tile += gdim_()) {
;         const int row0 = tile * 128, nloc = tile % TPB;
;         for (int it = tid; it < 128 * 32; it += 512) {
;             const int t = it >> 5, c8 = (it & 31) * 8;
;             float a[8];
; #pragma unroll
;             for (int e = 0; e < 8; ++e) a[e] = p.in[15][l * 256 + c8 + e];
; #pragma unroll
;             for (int k = 0; k < 4; ++k) {
;                 const int tt = t - 3 + k;
;                 if (nloc * 128 + tt < 0) continue;
;                 const u32x4 x = *(const u32x4*)(proj + (size_t)(row0 + tt) * DIN + 1024 + c8);
;                 const f32x4 w0 = *(const f32x4*)(p.in[14] + ((size_t)l * 4 + k) * 256 + c8), w1 = *(const f32x4*)(p.in[14] + ((size_t)l * 4 + k) * 256 + c8 + 4);
;                 a[0] += w0[0] * bflo(x.x); a[1] += w0[1] * bfhi(x.x); a[2] += w0[2] * bflo(x.y); a[3] += w0[3] * bfhi(x.y);
;                 a[4] += w1[0] * bflo(x.z); a[5] += w1[1] * bfhi(x.z); a[6] += w1[2] * bflo(x.w); a[7] += w1[3] * bfhi(x.w);
;             }
;             u32x4 o; o.x = pk2(a[0], a[1]); o.y = pk2(a[2], a[3]); o.z = pk2(a[4], a[5]); o.w = pk2(a[6], a[7]);
;             *(u32x4*)(xc + t * 264 + c8) = o;
;         }
.LBB0_1027:
	s_ashr_i32 s1, s0, 31
	s_lshr_b32 s14, s1, 25
	s_add_i32 s14, s0, s14
	s_and_b32 s14, s14, 0xffffff80
	s_lshl_b32 s40, s0, 7
	s_sub_i32 s30, s0, s14
	s_and_saveexec_b64 s[14:15], s[2:3]
	s_cbranch_execz .LBB0_1038
	s_lshl_b32 s26, s30, 7
	s_sub_i32 s31, 0, s26
	s_add_i32 s41, s40, -1
	s_mov_b64 s[26:27], 0
	v_and_b32_e32 v174, 0xf8, v153
	v_lshlrev_b32_e32 v232, 1, v174
	v_mov_b32_e32 v233, 0
	v_lshlrev_b32_e32 v174, 2, v174
	global_load_dwordx4 v[0:3], v174, s[94:95] offset:1024
	global_load_dwordx4 v[4:7], v174, s[94:95] offset:1040
	global_load_dwordx4 v[8:11], v174, s[24:25]
	global_load_dwordx4 v[12:15], v174, s[24:25] offset:16
	global_load_dwordx4 v[16:19], v174, s[24:25] offset:1024
	global_load_dwordx4 v[20:23], v174, s[24:25] offset:1040
	global_load_dwordx4 v[176:179], v174, s[24:25] offset:2048
	global_load_dwordx4 v[180:183], v174, s[24:25] offset:2064
	global_load_dwordx4 v[184:187], v174, s[24:25] offset:3072
	global_load_dwordx4 v[188:191], v174, s[24:25] offset:3088
	v_ashrrev_i32_e32 v175, 5, v142
	v_add_u32_e32 v250, s40, v175
	v_add_u32_e32 v250, -3, v250
	v_mov_b64_e32 v[24:25], s[52:53]
	v_mad_i64_i32 v[24:25], s[42:43], v250, s37, v[24:25]
	v_lshl_add_u64 v[24:25], v[24:25], 0, v[232:233]
	s_mov_b64 s[98:99], 0x800
	v_lshl_add_u64 v[24:25], v[24:25], 0, s[98:99]
	s_mov_b64 s[98:99], 0x1800
	v_lshl_add_u64 v[26:27], v[24:25], 0, s[98:99]
	s_mov_b64 s[98:99], 0xc000
	v_mul_lo_u32 v234, v175, s36
	v_add3_u32 v234, s34, v234, v232
	global_load_dwordx4 v[192:195], v[24:25], off
	global_load_dwordx4 v[196:199], v[24:25], off offset:3072
	global_load_dwordx4 v[200:203], v[26:27], off
	global_load_dwordx4 v[204:207], v[26:27], off offset:3072
	v_lshl_add_u64 v[24:25], v[24:25], 0, s[98:99]
	v_lshl_add_u64 v[26:27], v[26:27], 0, s[98:99]
	global_load_dwordx4 v[208:211], v[24:25], off
	global_load_dwordx4 v[212:215], v[24:25], off offset:3072
	global_load_dwordx4 v[216:219], v[26:27], off
	global_load_dwordx4 v[220:223], v[26:27], off offset:3072
	v_lshl_add_u64 v[24:25], v[24:25], 0, s[98:99]
	v_lshl_add_u64 v[26:27], v[26:27], 0, s[98:99]
	s_waitcnt vmcnt(4)
	v_add_u32_e32 v28, -3, v175
	v_cmp_le_i32_e32 vcc, s31, v28
	s_nop 1
	v_cndmask_b32_e32 v192, 0, v192, vcc
	v_cndmask_b32_e32 v193, 0, v193, vcc
	v_cndmask_b32_e32 v194, 0, v194, vcc
	v_cndmask_b32_e32 v195, 0, v195, vcc
	v_add_u32_e32 v28, -2, v175
	v_cmp_le_i32_e32 vcc, s31, v28
	s_nop 1
	v_cndmask_b32_e32 v196, 0, v196, vcc
	v_cndmask_b32_e32 v197, 0, v197, vcc
	v_cndmask_b32_e32 v198, 0, v198, vcc
	v_cndmask_b32_e32 v199, 0, v199, vcc
	v_add_u32_e32 v28, -1, v175
	v_cmp_le_i32_e32 vcc, s31, v28
	s_nop 1
	v_cndmask_b32_e32 v200, 0, v200, vcc
	v_cndmask_b32_e32 v201, 0, v201, vcc
	v_cndmask_b32_e32 v202, 0, v202, vcc
	v_cndmask_b32_e32 v203, 0, v203, vcc
	v_mov_b64_e32 v[224:225], v[0:1]
	v_mov_b64_e32 v[226:227], v[2:3]
	v_mov_b64_e32 v[228:229], v[4:5]
	v_mov_b64_e32 v[230:231], v[6:7]
	v_lshlrev_b32_e32 v28, 16, v192
	v_and_b32_e32 v29, 0xffff0000, v192
	v_pk_fma_f32 v[224:225], v[8:9], v[28:29], v[224:225]
	v_lshlrev_b32_e32 v28, 16, v193
	v_and_b32_e32 v29, 0xffff0000, v193
	v_pk_fma_f32 v[226:227], v[10:11], v[28:29], v[226:227]
	v_lshlrev_b32_e32 v28, 16, v194
	v_and_b32_e32 v29, 0xffff0000, v194
	v_pk_fma_f32 v[228:229], v[12:13], v[28:29], v[228:229]
	v_lshlrev_b32_e32 v28, 16, v195
	v_and_b32_e32 v29, 0xffff0000, v195
	v_pk_fma_f32 v[230:231], v[14:15], v[28:29], v[230:231]
	v_lshlrev_b32_e32 v28, 16, v196
	v_and_b32_e32 v29, 0xffff0000, v196
	v_pk_fma_f32 v[224:225], v[16:17], v[28:29], v[224:225]
	v_lshlrev_b32_e32 v28, 16, v197
	v_and_b32_e32 v29, 0xffff0000, v197
	v_pk_fma_f32 v[226:227], v[18:19], v[28:29], v[226:227]
	v_lshlrev_b32_e32 v28, 16, v198
	v_and_b32_e32 v29, 0xffff0000, v198
	v_pk_fma_f32 v[228:229], v[20:21], v[28:29], v[228:229]
	v_lshlrev_b32_e32 v28, 16, v199
	v_and_b32_e32 v29, 0xffff0000, v199
	v_pk_fma_f32 v[230:231], v[22:23], v[28:29], v[230:231]
	v_lshlrev_b32_e32 v28, 16, v200
	v_and_b32_e32 v29, 0xffff0000, v200
	v_pk_fma_f32 v[224:225], v[176:177], v[28:29], v[224:225]
	v_lshlrev_b32_e32 v28, 16, v201
	v_and_b32_e32 v29, 0xffff0000, v201
	v_pk_fma_f32 v[226:227], v[178:179], v[28:29], v[226:227]
	v_lshlrev_b32_e32 v28, 16, v202
	v_and_b32_e32 v29, 0xffff0000, v202
	v_pk_fma_f32 v[228:229], v[180:181], v[28:29], v[228:229]
	v_lshlrev_b32_e32 v28, 16, v203
	v_and_b32_e32 v29, 0xffff0000, v203
	v_pk_fma_f32 v[230:231], v[182:183], v[28:29], v[230:231]
	v_lshlrev_b32_e32 v28, 16, v204
	v_and_b32_e32 v29, 0xffff0000, v204
	v_pk_fma_f32 v[224:225], v[184:185], v[28:29], v[224:225]
	v_lshlrev_b32_e32 v28, 16, v205
	v_and_b32_e32 v29, 0xffff0000, v205
	v_pk_fma_f32 v[226:227], v[186:187], v[28:29], v[226:227]
	v_lshlrev_b32_e32 v28, 16, v206
	v_and_b32_e32 v29, 0xffff0000, v206
	v_pk_fma_f32 v[228:229], v[188:189], v[28:29], v[228:229]
	v_lshlrev_b32_e32 v28, 16, v207
	v_and_b32_e32 v29, 0xffff0000, v207
	v_pk_fma_f32 v[230:231], v[190:191], v[28:29], v[230:231]
	v_cvt_pk_bf16_f32 v224, v224, v225
	v_cvt_pk_bf16_f32 v225, v226, v227
	v_cvt_pk_bf16_f32 v226, v228, v229
	v_cvt_pk_bf16_f32 v227, v230, v231
	ds_write_b128 v234, v[224:227]
	s_waitcnt vmcnt(0)
	s_waitcnt lgkmcnt(0)
; DEVI unsigned pk2(float lo, float hi) { unsigned r; asm("v_cvt_pk_bf16_f32 %0, %1, %2" : "=v"(r) : "v"(lo), "v"(hi)); return r; }
; DEVI float bflo(unsigned w) { return __uint_as_float(w << 16); }
; DEVI float bfhi(unsigned w) { return __uint_as_float(w & 0xffff0000u); }
; DEVI void phase_m1(const Params& p, int l, unsigned char* smem) {
;     ...
;         for (int it = tid; it < 128 * 32; it += 512) {
;             const int t = it >> 5, c8 = (it & 31) * 8;
;             float a[8];
; #pragma unroll
;             for (int e = 0; e < 8; ++e) a[e] = p.in[15][l * 256 + c8 + e];
; #pragma unroll
;             for (int k = 0; k < 4; ++k) {
;                 const int tt = t - 3 + k;
;                 if (nloc * 128 + tt < 0) continue;
;                 const u32x4 x = *(const u32x4*)(proj + (size_t)(row0 + tt) * DIN + 1024 + c8);
;                 const f32x4 w0 = *(const f32x4*)(p.in[14] + ((size_t)l * 4 + k) * 256 + c8), w1 = *(const f32x4*)(p.in[14] + ((size_t)l * 4 + k) * 256 + c8 + 4);
;                 a[0] += w0[0] * bflo(x.x); a[1] += w0[1] * bfhi(x.x); a[2] += w0[2] * bflo(x.y); a[3] += w0[3] * bfhi(x.y);
;                 a[4] += w1[0] * bflo(x.z); a[5] += w1[1] * bfhi(x.z); a[6] += w1[2] * bflo(x.w); a[7] += w1[3] * bfhi(x.w);
;             }
;             u32x4 o; o.x = pk2(a[0], a[1]); o.y = pk2(a[2], a[3]); o.z = pk2(a[4], a[5]); o.w = pk2(a[6], a[7]);
;             *(u32x4*)(xc + t * 264 + c8) = o;
;         }
	v_mov_b64_e32 v[224:225], v[0:1]
	v_mov_b64_e32 v[226:227], v[2:3]
	v_mov_b64_e32 v[228:229], v[4:5]
	v_mov_b64_e32 v[230:231], v[6:7]
	v_lshlrev_b32_e32 v28, 16, v208
	v_and_b32_e32 v29, 0xffff0000, v208
	v_pk_fma_f32 v[224:225], v[8:9], v[28:29], v[224:225]
	v_lshlrev_b32_e32 v28, 16, v209
	v_and_b32_e32 v29, 0xffff0000, v209
	v_pk_fma_f32 v[226:227], v[10:11], v[28:29], v[226:227]
	v_lshlrev_b32_e32 v28, 16, v210
	v_and_b32_e32 v29, 0xffff0000, v210
	v_pk_fma_f32 v[228:229], v[12:13], v[28:29], v[228:229]
	v_lshlrev_b32_e32 v28, 16, v211
	v_and_b32_e32 v29, 0xffff0000, v211
	v_pk_fma_f32 v[230:231], v[14:15], v[28:29], v[230:231]
	v_lshlrev_b32_e32 v28, 16, v212
	v_and_b32_e32 v29, 0xffff0000, v212
	v_pk_fma_f32 v[224:225], v[16:17], v[28:29], v[224:225]
	v_lshlrev_b32_e32 v28, 16, v213
	v_and_b32_e32 v29, 0xffff0000, v213
	v_pk_fma_f32 v[226:227], v[18:19], v[28:29], v[226:227]
	v_lshlrev_b32_e32 v28, 16, v214
	v_and_b32_e32 v29, 0xffff0000, v214
	v_pk_fma_f32 v[228:229], v[20:21], v[28:29], v[228:229]
	v_lshlrev_b32_e32 v28, 16, v215
	v_and_b32_e32 v29, 0xffff0000, v215
	v_pk_fma_f32 v[230:231], v[22:23], v[28:29], v[230:231]
	v_lshlrev_b32_e32 v28, 16, v216
	v_and_b32_e32 v29, 0xffff0000, v216
	v_pk_fma_f32 v[224:225], v[176:177], v[28:29], v[224:225]
	v_lshlrev_b32_e32 v28, 16, v217
	v_and_b32_e32 v29, 0xffff0000, v217
	v_pk_fma_f32 v[226:227], v[178:179], v[28:29], v[226:227]
	v_lshlrev_b32_e32 v28, 16, v218
	v_and_b32_e32 v29, 0xffff0000, v218
	v_pk_fma_f32 v[228:229], v[180:181], v[28:29], v[228:229]
	v_lshlrev_b32_e32 v28, 16, v219
	v_and_b32_e32 v29, 0xffff0000, v219
	v_pk_fma_f32 v[230:231], v[182:183], v[28:29], v[230:231]
	v_lshlrev_b32_e32 v28, 16, v220
	v_and_b32_e32 v29, 0xffff0000, v220
	v_pk_fma_f32 v[224:225], v[184:185], v[28:29], v[224:225]
	v_lshlrev_b32_e32 v28, 16, v221
	v_and_b32_e32 v29, 0xffff0000, v221
	v_pk_fma_f32 v[226:227], v[186:187], v[28:29], v[226:227]
	v_lshlrev_b32_e32 v28, 16, v222
	v_and_b32_e32 v29, 0xffff0000, v222
	v_pk_fma_f32 v[228:229], v[188:189], v[28:29], v[228:229]
	v_lshlrev_b32_e32 v28, 16, v223
	v_and_b32_e32 v29, 0xffff0000, v223
	v_pk_fma_f32 v[230:231], v[190:191], v[28:29], v[230:231]
	v_cvt_pk_bf16_f32 v224, v224, v225
	v_cvt_pk_bf16_f32 v225, v226, v227
	v_cvt_pk_bf16_f32 v226, v228, v229
	v_cvt_pk_bf16_f32 v227, v230, v231
	ds_write_b128 v234, v[224:227] offset:8448
	global_load_dwordx4 v[192:195], v[24:25], off
	global_load_dwordx4 v[196:199], v[24:25], off offset:3072
	global_load_dwordx4 v[200:203], v[26:27], off
	global_load_dwordx4 v[204:207], v[26:27], off offset:3072
	v_lshl_add_u64 v[24:25], v[24:25], 0, s[98:99]
	v_lshl_add_u64 v[26:27], v[26:27], 0, s[98:99]
	global_load_dwordx4 v[208:211], v[24:25], off
	global_load_dwordx4 v[212:215], v[24:25], off offset:3072
	global_load_dwordx4 v[216:219], v[26:27], off
	global_load_dwordx4 v[220:223], v[26:27], off offset:3072
	v_lshl_add_u64 v[24:25], v[24:25], 0, s[98:99]
	v_lshl_add_u64 v[26:27], v[26:27], 0, s[98:99]
	s_waitcnt vmcnt(4)
	s_waitcnt lgkmcnt(0)
	v_mov_b64_e32 v[224:225], v[0:1]
	v_mov_b64_e32 v[226:227], v[2:3]
	v_mov_b64_e32 v[228:229], v[4:5]
	v_mov_b64_e32 v[230:231], v[6:7]
	v_lshlrev_b32_e32 v28, 16, v192
	v_and_b32_e32 v29, 0xffff0000, v192
	v_pk_fma_f32 v[224:225], v[8:9], v[28:29], v[224:225]
	v_lshlrev_b32_e32 v28, 16, v193
	v_and_b32_e32 v29, 0xffff0000, v193
	v_pk_fma_f32 v[226:227], v[10:11], v[28:29], v[226:227]
	v_lshlrev_b32_e32 v28, 16, v194
	v_and_b32_e32 v29, 0xffff0000, v194
	v_pk_fma_f32 v[228:229], v[12:13], v[28:29], v[228:229]
	v_lshlrev_b32_e32 v28, 16, v195
	v_and_b32_e32 v29, 0xffff0000, v195
	v_pk_fma_f32 v[230:231], v[14:15], v[28:29], v[230:231]
	v_lshlrev_b32_e32 v28, 16, v196
	v_and_b32_e32 v29, 0xffff0000, v196
	v_pk_fma_f32 v[224:225], v[16:17], v[28:29], v[224:225]
	v_lshlrev_b32_e32 v28, 16, v197
	v_and_b32_e32 v29, 0xffff0000, v197
	v_pk_fma_f32 v[226:227], v[18:19], v[28:29], v[226:227]
	v_lshlrev_b32_e32 v28, 16, v198
	v_and_b32_e32 v29, 0xffff0000, v198
	v_pk_fma_f32 v[228:229], v[20:21], v[28:29], v[228:229]
	v_lshlrev_b32_e32 v28, 16, v199
	v_and_b32_e32 v29, 0xffff0000, v199
	v_pk_fma_f32 v[230:231], v[22:23], v[28:29], v[230:231]
	v_lshlrev_b32_e32 v28, 16, v200
	v_and_b32_e32 v29, 0xffff0000, v200
	v_pk_fma_f32 v[224:225], v[176:177], v[28:29], v[224:225]
	v_lshlrev_b32_e32 v28, 16, v201
	v_and_b32_e32 v29, 0xffff0000, v201
	v_pk_fma_f32 v[226:227], v[178:179], v[28:29], v[226:227]
	v_lshlrev_b32_e32 v28, 16, v202
	v_and_b32_e32 v29, 0xffff0000, v202
	v_pk_fma_f32 v[228:229], v[180:181], v[28:29], v[228:229]
	v_lshlrev_b32_e32 v28, 16, v203
	v_and_b32_e32 v29, 0xffff0000, v203
	v_pk_fma_f32 v[230:231], v[182:183], v[28:29], v[230:231]
	v_lshlrev_b32_e32 v28, 16, v204
	v_and_b32_e32 v29, 0xffff0000, v204
	v_pk_fma_f32 v[224:225], v[184:185], v[28:29], v[224:225]
	v_lshlrev_b32_e32 v28, 16, v205
	v_and_b32_e32 v29, 0xffff0000, v205
	v_pk_fma_f32 v[226:227], v[186:187], v[28:29], v[226:227]
	v_lshlrev_b32_e32 v28, 16, v206
	v_and_b32_e32 v29, 0xffff0000, v206
	v_pk_fma_f32 v[228:229], v[188:189], v[28:29], v[228:229]
	v_lshlrev_b32_e32 v28, 16, v207
	v_and_b32_e32 v29, 0xffff0000, v207
	v_pk_fma_f32 v[230:231], v[190:191], v[28:29], v[230:231]
	v_cvt_pk_bf16_f32 v224, v224, v225
	v_cvt_pk_bf16_f32 v225, v226, v227
	v_cvt_pk_bf16_f32 v226, v228, v229
	v_cvt_pk_bf16_f32 v227, v230, v231
	ds_write_b128 v234, v[224:227] offset:16896
	s_waitcnt vmcnt(0)
	s_waitcnt lgkmcnt(0)
; DEVI unsigned pk2(float lo, float hi) { unsigned r; asm("v_cvt_pk_bf16_f32 %0, %1, %2" : "=v"(r) : "v"(lo), "v"(hi)); return r; }
; DEVI float bflo(unsigned w) { return __uint_as_float(w << 16); }
; DEVI float bfhi(unsigned w) { return __uint_as_float(w & 0xffff0000u); }
; DEVI void phase_m1(const Params& p, int l, unsigned char* smem) {
;     ...
;         for (int it = tid; it < 128 * 32; it += 512) {
;             const int t = it >> 5, c8 = (it & 31) * 8;
;             float a[8];
; #pragma unroll
;             for (int e = 0; e < 8; ++e) a[e] = p.in[15][l * 256 + c8 + e];
; #pragma unroll
;             for (int k = 0; k < 4; ++k) {
;                 const int tt = t - 3 + k;
;                 if (nloc * 128 + tt < 0) continue;
;                 const u32x4 x = *(const u32x4*)(proj + (size_t)(row0 + tt) * DIN + 1024 + c8);
;                 const f32x4 w0 = *(const f32x4*)(p.in[14] + ((size_t)l * 4 + k) * 256 + c8), w1 = *(const f32x4*)(p.in[14] + ((size_t)l * 4 + k) * 256 + c8 + 4);
;                 a[0] += w0[0] * bflo(x.x); a[1] += w0[1] * bfhi(x.x); a[2] += w0[2] * bflo(x.y); a[3] += w0[3] * bfhi(x.y);
;                 a[4] += w1[0] * bflo(x.z); a[5] += w1[1] * bfhi(x.z); a[6] += w1[2] * bflo(x.w); a[7] += w1[3] * bfhi(x.w);
;             }
;             u32x4 o; o.x = pk2(a[0], a[1]); o.y = pk2(a[2], a[3]); o.z = pk2(a[4], a[5]); o.w = pk2(a[6], a[7]);
;             *(u32x4*)(xc + t * 264 + c8) = o;
;         }
	v_mov_b64_e32 v[224:225], v[0:1]
	v_mov_b64_e32 v[226:227], v[2:3]
	v_mov_b64_e32 v[228:229], v[4:5]
	v_mov_b64_e32 v[230:231], v[6:7]
	v_lshlrev_b32_e32 v28, 16, v208
	v_and_b32_e32 v29, 0xffff0000, v208
	v_pk_fma_f32 v[224:225], v[8:9], v[28:29], v[224:225]
	v_lshlrev_b32_e32 v28, 16, v209
	v_and_b32_e32 v29, 0xffff0000, v209
	v_pk_fma_f32 v[226:227], v[10:11], v[28:29], v[226:227]
	v_lshlrev_b32_e32 v28, 16, v210
	v_and_b32_e32 v29, 0xffff0000, v210
	v_pk_fma_f32 v[228:229], v[12:13], v[28:29], v[228:229]
	v_lshlrev_b32_e32 v28, 16, v211
	v_and_b32_e32 v29, 0xffff0000, v211
	v_pk_fma_f32 v[230:231], v[14:15], v[28:29], v[230:231]
	v_lshlrev_b32_e32 v28, 16, v212
	v_and_b32_e32 v29, 0xffff0000, v212
	v_pk_fma_f32 v[224:225], v[16:17], v[28:29], v[224:225]
	v_lshlrev_b32_e32 v28, 16, v213
	v_and_b32_e32 v29, 0xffff0000, v213
	v_pk_fma_f32 v[226:227], v[18:19], v[28:29], v[226:227]
	v_lshlrev_b32_e32 v28, 16, v214
	v_and_b32_e32 v29, 0xffff0000, v214
	v_pk_fma_f32 v[228:229], v[20:21], v[28:29], v[228:229]
	v_lshlrev_b32_e32 v28, 16, v215
	v_and_b32_e32 v29, 0xffff0000, v215
	v_pk_fma_f32 v[230:231], v[22:23], v[28:29], v[230:231]
	v_lshlrev_b32_e32 v28, 16, v216
	v_and_b32_e32 v29, 0xffff0000, v216
	v_pk_fma_f32 v[224:225], v[176:177], v[28:29], v[224:225]
	v_lshlrev_b32_e32 v28, 16, v217
	v_and_b32_e32 v29, 0xffff0000, v217
	v_pk_fma_f32 v[226:227], v[178:179], v[28:29], v[226:227]
	v_lshlrev_b32_e32 v28, 16, v218
	v_and_b32_e32 v29, 0xffff0000, v218
	v_pk_fma_f32 v[228:229], v[180:181], v[28:29], v[228:229]
	v_lshlrev_b32_e32 v28, 16, v219
	v_and_b32_e32 v29, 0xffff0000, v219
	v_pk_fma_f32 v[230:231], v[182:183], v[28:29], v[230:231]
	v_lshlrev_b32_e32 v28, 16, v220
	v_and_b32_e32 v29, 0xffff0000, v220
	v_pk_fma_f32 v[224:225], v[184:185], v[28:29], v[224:225]
	v_lshlrev_b32_e32 v28, 16, v221
	v_and_b32_e32 v29, 0xffff0000, v221
	v_pk_fma_f32 v[226:227], v[186:187], v[28:29], v[226:227]
	v_lshlrev_b32_e32 v28, 16, v222
	v_and_b32_e32 v29, 0xffff0000, v222
	v_pk_fma_f32 v[228:229], v[188:189], v[28:29], v[228:229]
	v_lshlrev_b32_e32 v28, 16, v223
	v_and_b32_e32 v29, 0xffff0000, v223
	v_pk_fma_f32 v[230:231], v[190:191], v[28:29], v[230:231]
	v_cvt_pk_bf16_f32 v224, v224, v225
	v_cvt_pk_bf16_f32 v225, v226, v227
	v_cvt_pk_bf16_f32 v226, v228, v229
	v_cvt_pk_bf16_f32 v227, v230, v231
	ds_write_b128 v234, v[224:227] offset:25344
	global_load_dwordx4 v[192:195], v[24:25], off
	global_load_dwordx4 v[196:199], v[24:25], off offset:3072
	global_load_dwordx4 v[200:203], v[26:27], off
	global_load_dwordx4 v[204:207], v[26:27], off offset:3072
	v_lshl_add_u64 v[24:25], v[24:25], 0, s[98:99]
	v_lshl_add_u64 v[26:27], v[26:27], 0, s[98:99]
	global_load_dwordx4 v[208:211], v[24:25], off
	global_load_dwordx4 v[212:215], v[24:25], off offset:3072
	global_load_dwordx4 v[216:219], v[26:27], off
	global_load_dwordx4 v[220:223], v[26:27], off offset:3072
	v_lshl_add_u64 v[24:25], v[24:25], 0, s[98:99]
	v_lshl_add_u64 v[26:27], v[26:27], 0, s[98:99]
	s_waitcnt vmcnt(4)
	s_waitcnt lgkmcnt(0)
	v_mov_b64_e32 v[224:225], v[0:1]
	v_mov_b64_e32 v[226:227], v[2:3]
	v_mov_b64_e32 v[228:229], v[4:5]
	v_mov_b64_e32 v[230:231], v[6:7]
	v_lshlrev_b32_e32 v28, 16, v192
	v_and_b32_e32 v29, 0xffff0000, v192
	v_pk_fma_f32 v[224:225], v[8:9], v[28:29], v[224:225]
	v_lshlrev_b32_e32 v28, 16, v193
	v_and_b32_e32 v29, 0xffff0000, v193
	v_pk_fma_f32 v[226:227], v[10:11], v[28:29], v[226:227]
	v_lshlrev_b32_e32 v28, 16, v194
	v_and_b32_e32 v29, 0xffff0000, v194
	v_pk_fma_f32 v[228:229], v[12:13], v[28:29], v[228:229]
	v_lshlrev_b32_e32 v28, 16, v195
	v_and_b32_e32 v29, 0xffff0000, v195
	v_pk_fma_f32 v[230:231], v[14:15], v[28:29], v[230:231]
	v_lshlrev_b32_e32 v28, 16, v196
	v_and_b32_e32 v29, 0xffff0000, v196
	v_pk_fma_f32 v[224:225], v[16:17], v[28:29], v[224:225]
	v_lshlrev_b32_e32 v28, 16, v197
	v_and_b32_e32 v29, 0xffff0000, v197
	v_pk_fma_f32 v[226:227], v[18:19], v[28:29], v[226:227]
	v_lshlrev_b32_e32 v28, 16, v198
	v_and_b32_e32 v29, 0xffff0000, v198
	v_pk_fma_f32 v[228:229], v[20:21], v[28:29], v[228:229]
	v_lshlrev_b32_e32 v28, 16, v199
	v_and_b32_e32 v29, 0xffff0000, v199
	v_pk_fma_f32 v[230:231], v[22:23], v[28:29], v[230:231]
	v_lshlrev_b32_e32 v28, 16, v200
	v_and_b32_e32 v29, 0xffff0000, v200
	v_pk_fma_f32 v[224:225], v[176:177], v[28:29], v[224:225]
	v_lshlrev_b32_e32 v28, 16, v201
	v_and_b32_e32 v29, 0xffff0000, v201
	v_pk_fma_f32 v[226:227], v[178:179], v[28:29], v[226:227]
	v_lshlrev_b32_e32 v28, 16, v202
	v_and_b32_e32 v29, 0xffff0000, v202
	v_pk_fma_f32 v[228:229], v[180:181], v[28:29], v[228:229]
	v_lshlrev_b32_e32 v28, 16, v203
	v_and_b32_e32 v29, 0xffff0000, v203
	v_pk_fma_f32 v[230:231], v[182:183], v[28:29], v[230:231]
	v_lshlrev_b32_e32 v28, 16, v204
	v_and_b32_e32 v29, 0xffff0000, v204
	v_pk_fma_f32 v[224:225], v[184:185], v[28:29], v[224:225]
	v_lshlrev_b32_e32 v28, 16, v205
	v_and_b32_e32 v29, 0xffff0000, v205
	v_pk_fma_f32 v[226:227], v[186:187], v[28:29], v[226:227]
	v_lshlrev_b32_e32 v28, 16, v206
	v_and_b32_e32 v29, 0xffff0000, v206
	v_pk_fma_f32 v[228:229], v[188:189], v[28:29], v[228:229]
	v_lshlrev_b32_e32 v28, 16, v207
	v_and_b32_e32 v29, 0xffff0000, v207
	v_pk_fma_f32 v[230:231], v[190:191], v[28:29], v[230:231]
	v_cvt_pk_bf16_f32 v224, v224, v225
	v_cvt_pk_bf16_f32 v225, v226, v227
	v_cvt_pk_bf16_f32 v226, v228, v229
	v_cvt_pk_bf16_f32 v227, v230, v231
	ds_write_b128 v234, v[224:227] offset:33792
	s_waitcnt vmcnt(0)
	s_waitcnt lgkmcnt(0)
; DEVI unsigned pk2(float lo, float hi) { unsigned r; asm("v_cvt_pk_bf16_f32 %0, %1, %2" : "=v"(r) : "v"(lo), "v"(hi)); return r; }
; DEVI float bflo(unsigned w) { return __uint_as_float(w << 16); }
; DEVI float bfhi(unsigned w) { return __uint_as_float(w & 0xffff0000u); }
; DEVI void phase_m1(const Params& p, int l, unsigned char* smem) {
;     ...
;         for (int it = tid; it < 128 * 32; it += 512) {
;             const int t = it >> 5, c8 = (it & 31) * 8;
;             float a[8];
; #pragma unroll
;             for (int e = 0; e < 8; ++e) a[e] = p.in[15][l * 256 + c8 + e];
; #pragma unroll
;             for (int k = 0; k < 4; ++k) {
;                 const int tt = t - 3 + k;
;                 if (nloc * 128 + tt < 0) continue;
;                 const u32x4 x = *(const u32x4*)(proj + (size_t)(row0 + tt) * DIN + 1024 + c8);
;                 const f32x4 w0 = *(const f32x4*)(p.in[14] + ((size_t)l * 4 + k) * 256 + c8), w1 = *(const f32x4*)(p.in[14] + ((size_t)l * 4 + k) * 256 + c8 + 4);
;                 a[0] += w0[0] * bflo(x.x); a[1] += w0[1] * bfhi(x.x); a[2] += w0[2] * bflo(x.y); a[3] += w0[3] * bfhi(x.y);
;                 a[4] += w1[0] * bflo(x.z); a[5] += w1[1] * bfhi(x.z); a[6] += w1[2] * bflo(x.w); a[7] += w1[3] * bfhi(x.w);
;             }
;             u32x4 o; o.x = pk2(a[0], a[1]); o.y = pk2(a[2], a[3]); o.z = pk2(a[4], a[5]); o.w = pk2(a[6], a[7]);
;             *(u32x4*)(xc + t * 264 + c8) = o;
;         }
	v_mov_b64_e32 v[224:225], v[0:1]
	v_mov_b64_e32 v[226:227], v[2:3]
	v_mov_b64_e32 v[228:229], v[4:5]
	v_mov_b64_e32 v[230:231], v[6:7]
	v_lshlrev_b32_e32 v28, 16, v208
	v_and_b32_e32 v29, 0xffff0000, v208
	v_pk_fma_f32 v[224:225], v[8:9], v[28:29], v[224:225]
	v_lshlrev_b32_e32 v28, 16, v209
	v_and_b32_e32 v29, 0xffff0000, v209
	v_pk_fma_f32 v[226:227], v[10:11], v[28:29], v[226:227]
	v_lshlrev_b32_e32 v28, 16, v210
	v_and_b32_e32 v29, 0xffff0000, v210
	v_pk_fma_f32 v[228:229], v[12:13], v[28:29], v[228:229]
	v_lshlrev_b32_e32 v28, 16, v211
	v_and_b32_e32 v29, 0xffff0000, v211
	v_pk_fma_f32 v[230:231], v[14:15], v[28:29], v[230:231]
	v_lshlrev_b32_e32 v28, 16, v212
	v_and_b32_e32 v29, 0xffff0000, v212
	v_pk_fma_f32 v[224:225], v[16:17], v[28:29], v[224:225]
	v_lshlrev_b32_e32 v28, 16, v213
	v_and_b32_e32 v29, 0xffff0000, v213
	v_pk_fma_f32 v[226:227], v[18:19], v[28:29], v[226:227]
	v_lshlrev_b32_e32 v28, 16, v214
	v_and_b32_e32 v29, 0xffff0000, v214
	v_pk_fma_f32 v[228:229], v[20:21], v[28:29], v[228:229]
	v_lshlrev_b32_e32 v28, 16, v215
	v_and_b32_e32 v29, 0xffff0000, v215
	v_pk_fma_f32 v[230:231], v[22:23], v[28:29], v[230:231]
	v_lshlrev_b32_e32 v28, 16, v216
	v_and_b32_e32 v29, 0xffff0000, v216
	v_pk_fma_f32 v[224:225], v[176:177], v[28:29], v[224:225]
	v_lshlrev_b32_e32 v28, 16, v217
	v_and_b32_e32 v29, 0xffff0000, v217
	v_pk_fma_f32 v[226:227], v[178:179], v[28:29], v[226:227]
	v_lshlrev_b32_e32 v28, 16, v218
	v_and_b32_e32 v29, 0xffff0000, v218
	v_pk_fma_f32 v[228:229], v[180:181], v[28:29], v[228:229]
	v_lshlrev_b32_e32 v28, 16, v219
	v_and_b32_e32 v29, 0xffff0000, v219
	v_pk_fma_f32 v[230:231], v[182:183], v[28:29], v[230:231]
	v_lshlrev_b32_e32 v28, 16, v220
	v_and_b32_e32 v29, 0xffff0000, v220
	v_pk_fma_f32 v[224:225], v[184:185], v[28:29], v[224:225]
	v_lshlrev_b32_e32 v28, 16, v221
	v_and_b32_e32 v29, 0xffff0000, v221
	v_pk_fma_f32 v[226:227], v[186:187], v[28:29], v[226:227]
	v_lshlrev_b32_e32 v28, 16, v222
	v_and_b32_e32 v29, 0xffff0000, v222
	v_pk_fma_f32 v[228:229], v[188:189], v[28:29], v[228:229]
	v_lshlrev_b32_e32 v28, 16, v223
	v_and_b32_e32 v29, 0xffff0000, v223
	v_pk_fma_f32 v[230:231], v[190:191], v[28:29], v[230:231]
	v_cvt_pk_bf16_f32 v224, v224, v225
	v_cvt_pk_bf16_f32 v225, v226, v227
	v_cvt_pk_bf16_f32 v226, v228, v229
	v_cvt_pk_bf16_f32 v227, v230, v231
	ds_write_b128 v234, v[224:227] offset:42240
	global_load_dwordx4 v[192:195], v[24:25], off
	global_load_dwordx4 v[196:199], v[24:25], off offset:3072
	global_load_dwordx4 v[200:203], v[26:27], off
	global_load_dwordx4 v[204:207], v[26:27], off offset:3072
	v_lshl_add_u64 v[24:25], v[24:25], 0, s[98:99]
	v_lshl_add_u64 v[26:27], v[26:27], 0, s[98:99]
	global_load_dwordx4 v[208:211], v[24:25], off
	global_load_dwordx4 v[212:215], v[24:25], off offset:3072
	global_load_dwordx4 v[216:219], v[26:27], off
	global_load_dwordx4 v[220:223], v[26:27], off offset:3072
	v_lshl_add_u64 v[24:25], v[24:25], 0, s[98:99]
	v_lshl_add_u64 v[26:27], v[26:27], 0, s[98:99]
	s_waitcnt vmcnt(4)
	s_waitcnt lgkmcnt(0)
; DEVI unsigned pk2(float lo, float hi) { unsigned r; asm("v_cvt_pk_bf16_f32 %0, %1, %2" : "=v"(r) : "v"(lo), "v"(hi)); return r; }
; DEVI float bflo(unsigned w) { return __uint_as_float(w << 16); }
; DEVI float bfhi(unsigned w) { return __uint_as_float(w & 0xffff0000u); }
; DEVI void phase_m1(const Params& p, int l, unsigned char* smem) {
;     ...
;         for (int it = tid; it < 128 * 32; it += 512) {
;             const int t = it >> 5, c8 = (it & 31) * 8;
;             float a[8];
; #pragma unroll
;             for (int e = 0; e < 8; ++e) a[e] = p.in[15][l * 256 + c8 + e];
; #pragma unroll
;             for (int k = 0; k < 4; ++k) {
;                 const int tt = t - 3 + k;
;                 if (nloc * 128 + tt < 0) continue;
;                 const u32x4 x = *(const u32x4*)(proj + (size_t)(row0 + tt) * DIN + 1024 + c8);
;                 const f32x4 w0 = *(const f32x4*)(p.in[14] + ((size_t)l * 4 + k) * 256 + c8), w1 = *(const f32x4*)(p.in[14] + ((size_t)l * 4 + k) * 256 + c8 + 4);
;                 a[0] += w0[0] * bflo(x.x); a[1] += w0[1] * bfhi(x.x); a[2] += w0[2] * bflo(x.y); a[3] += w0[3] * bfhi(x.y);
;                 a[4] += w1[0] * bflo(x.z); a[5] += w1[1] * bfhi(x.z); a[6] += w1[2] * bflo(x.w); a[7] += w1[3] * bfhi(x.w);
;             }
;             u32x4 o; o.x = pk2(a[0], a[1]); o.y = pk2(a[2], a[3]); o.z = pk2(a[4], a[5]); o.w = pk2(a[6], a[7]);
;             *(u32x4*)(xc + t * 264 + c8) = o;
;         }
	v_mov_b64_e32 v[224:225], v[0:1]
	v_mov_b64_e32 v[226:227], v[2:3]
	v_mov_b64_e32 v[228:229], v[4:5]
	v_mov_b64_e32 v[230:231], v[6:7]
	v_lshlrev_b32_e32 v28, 16, v192
	v_and_b32_e32 v29, 0xffff0000, v192
	v_pk_fma_f32 v[224:225], v[8:9], v[28:29], v[224:225]
	v_lshlrev_b32_e32 v28, 16, v193
	v_and_b32_e32 v29, 0xffff0000, v193
	v_pk_fma_f32 v[226:227], v[10:11], v[28:29], v[226:227]
	v_lshlrev_b32_e32 v28, 16, v194
	v_and_b32_e32 v29, 0xffff0000, v194
	v_pk_fma_f32 v[228:229], v[12:13], v[28:29], v[228:229]
	v_lshlrev_b32_e32 v28, 16, v195
	v_and_b32_e32 v29, 0xffff0000, v195
	v_pk_fma_f32 v[230:231], v[14:15], v[28:29], v[230:231]
	v_lshlrev_b32_e32 v28, 16, v196
	v_and_b32_e32 v29, 0xffff0000, v196
	v_pk_fma_f32 v[224:225], v[16:17], v[28:29], v[224:225]
	v_lshlrev_b32_e32 v28, 16, v197
	v_and_b32_e32 v29, 0xffff0000, v197
	v_pk_fma_f32 v[226:227], v[18:19], v[28:29], v[226:227]
	v_lshlrev_b32_e32 v28, 16, v198
	v_and_b32_e32 v29, 0xffff0000, v198
	v_pk_fma_f32 v[228:229], v[20:21], v[28:29], v[228:229]
	v_lshlrev_b32_e32 v28, 16, v199
	v_and_b32_e32 v29, 0xffff0000, v199
	v_pk_fma_f32 v[230:231], v[22:23], v[28:29], v[230:231]
	v_lshlrev_b32_e32 v28, 16, v200
	v_and_b32_e32 v29, 0xffff0000, v200
	v_pk_fma_f32 v[224:225], v[176:177], v[28:29], v[224:225]
	v_lshlrev_b32_e32 v28, 16, v201
	v_and_b32_e32 v29, 0xffff0000, v201
	v_pk_fma_f32 v[226:227], v[178:179], v[28:29], v[226:227]
	v_lshlrev_b32_e32 v28, 16, v202
	v_and_b32_e32 v29, 0xffff0000, v202
	v_pk_fma_f32 v[228:229], v[180:181], v[28:29], v[228:229]
	v_lshlrev_b32_e32 v28, 16, v203
	v_and_b32_e32 v29, 0xffff0000, v203
	v_pk_fma_f32 v[230:231], v[182:183], v[28:29], v[230:231]
	v_lshlrev_b32_e32 v28, 16, v204
	v_and_b32_e32 v29, 0xffff0000, v204
	v_pk_fma_f32 v[224:225], v[184:185], v[28:29], v[224:225]
	v_lshlrev_b32_e32 v28, 16, v205
	v_and_b32_e32 v29, 0xffff0000, v205
	v_pk_fma_f32 v[226:227], v[186:187], v[28:29], v[226:227]
	v_lshlrev_b32_e32 v28, 16, v206
	v_and_b32_e32 v29, 0xffff0000, v206
	v_pk_fma_f32 v[228:229], v[188:189], v[28:29], v[228:229]
	v_lshlrev_b32_e32 v28, 16, v207
	v_and_b32_e32 v29, 0xffff0000, v207
	v_pk_fma_f32 v[230:231], v[190:191], v[28:29], v[230:231]
	v_cvt_pk_bf16_f32 v224, v224, v225
	v_cvt_pk_bf16_f32 v225, v226, v227
	v_cvt_pk_bf16_f32 v226, v228, v229
	v_cvt_pk_bf16_f32 v227, v230, v231
	ds_write_b128 v234, v[224:227] offset:50688
	s_waitcnt vmcnt(0)
	s_waitcnt lgkmcnt(0)
	v_mov_b64_e32 v[224:225], v[0:1]
	v_mov_b64_e32 v[226:227], v[2:3]
	v_mov_b64_e32 v[228:229], v[4:5]
	v_mov_b64_e32 v[230:231], v[6:7]
	v_lshlrev_b32_e32 v28, 16, v208
	v_and_b32_e32 v29, 0xffff0000, v208
	v_pk_fma_f32 v[224:225], v[8:9], v[28:29], v[224:225]
	v_lshlrev_b32_e32 v28, 16, v209
	v_and_b32_e32 v29, 0xffff0000, v209
	v_pk_fma_f32 v[226:227], v[10:11], v[28:29], v[226:227]
	v_lshlrev_b32_e32 v28, 16, v210
	v_and_b32_e32 v29, 0xffff0000, v210
	v_pk_fma_f32 v[228:229], v[12:13], v[28:29], v[228:229]
	v_lshlrev_b32_e32 v28, 16, v211
	v_and_b32_e32 v29, 0xffff0000, v211
	v_pk_fma_f32 v[230:231], v[14:15], v[28:29], v[230:231]
	v_lshlrev_b32_e32 v28, 16, v212
	v_and_b32_e32 v29, 0xffff0000, v212
	v_pk_fma_f32 v[224:225], v[16:17], v[28:29], v[224:225]
	v_lshlrev_b32_e32 v28, 16, v213
	v_and_b32_e32 v29, 0xffff0000, v213
	v_pk_fma_f32 v[226:227], v[18:19], v[28:29], v[226:227]
	v_lshlrev_b32_e32 v28, 16, v214
	v_and_b32_e32 v29, 0xffff0000, v214
	v_pk_fma_f32 v[228:229], v[20:21], v[28:29], v[228:229]
	v_lshlrev_b32_e32 v28, 16, v215
	v_and_b32_e32 v29, 0xffff0000, v215
	v_pk_fma_f32 v[230:231], v[22:23], v[28:29], v[230:231]
	v_lshlrev_b32_e32 v28, 16, v216
	v_and_b32_e32 v29, 0xffff0000, v216
	v_pk_fma_f32 v[224:225], v[176:177], v[28:29], v[224:225]
	v_lshlrev_b32_e32 v28, 16, v217
	v_and_b32_e32 v29, 0xffff0000, v217
	v_pk_fma_f32 v[226:227], v[178:179], v[28:29], v[226:227]
	v_lshlrev_b32_e32 v28, 16, v218
	v_and_b32_e32 v29, 0xffff0000, v218
	v_pk_fma_f32 v[228:229], v[180:181], v[28:29], v[228:229]
	v_lshlrev_b32_e32 v28, 16, v219
	v_and_b32_e32 v29, 0xffff0000, v219
	v_pk_fma_f32 v[230:231], v[182:183], v[28:29], v[230:231]
	v_lshlrev_b32_e32 v28, 16, v220
	v_and_b32_e32 v29, 0xffff0000, v220
	v_pk_fma_f32 v[224:225], v[184:185], v[28:29], v[224:225]
	v_lshlrev_b32_e32 v28, 16, v221
	v_and_b32_e32 v29, 0xffff0000, v221
	v_pk_fma_f32 v[226:227], v[186:187], v[28:29], v[226:227]
	v_lshlrev_b32_e32 v28, 16, v222
	v_and_b32_e32 v29, 0xffff0000, v222
	v_pk_fma_f32 v[228:229], v[188:189], v[28:29], v[228:229]
	v_lshlrev_b32_e32 v28, 16, v223
	v_and_b32_e32 v29, 0xffff0000, v223
	v_pk_fma_f32 v[230:231], v[190:191], v[28:29], v[230:231]
	v_cvt_pk_bf16_f32 v224, v224, v225
	v_cvt_pk_bf16_f32 v225, v226, v227
	v_cvt_pk_bf16_f32 v226, v228, v229
	v_cvt_pk_bf16_f32 v227, v230, v231
	ds_write_b128 v234, v[224:227] offset:59136

; DEVI int bid_() { int t = blockIdx.x; asm volatile("" : "+s"(t)); return t; }
; DEVI int gdim_() { int t = gridDim.x; asm volatile("" : "+s"(t)); return t; }
; DEVI unsigned pk2(float lo, float hi) { unsigned r; asm("v_cvt_pk_bf16_f32 %0, %1, %2" : "=v"(r) : "v"(lo), "v"(hi)); return r; }
; DEVI float bflo(unsigned w) { return __uint_as_float(w << 16); }
; DEVI float bfhi(unsigned w) { return __uint_as_float(w & 0xffff0000u); }
; DEVI void phase_m1(const Params& p, int l, unsigned char* smem) {
;     ...
;     for (int tile = bid_(); tile < NTILE; tile += gdim_()) {
;         const int row0 = tile * 128, nloc = tile % TPB;
;         for (int it = tid; it < 128 * 32; it += 512) {
;             const int t = it >> 5, c8 = (it & 31) * 8;
;             float a[8];
; #pragma unroll
;             for (int e = 0; e < 8; ++e) a[e] = p.in[15][l * 256 + c8 + e];
; #pragma unroll
;             for (int k = 0; k < 4; ++k) {
;                 const int tt = t - 3 + k;
;                 if (nloc * 128 + tt < 0) continue;
;                 const u32x4 x = *(const u32x4*)(proj + (size_t)(row0 + tt) * DIN + 1024 + c8);
;                 const f32x4 w0 = *(const f32x4*)(p.in[14] + ((size_t)l * 4 + k) * 256 + c8), w1 = *(const f32x4*)(p.in[14] + ((size_t)l * 4 + k) * 256 + c8 + 4);
;                 a[0] += w0[0] * bflo(x.x); a[1] += w0[1] * bfhi(x.x); a[2] += w0[2] * bflo(x.y); a[3] += w0[3] * bfhi(x.y);
;                 a[4] += w1[0] * bflo(x.z); a[5] += w1[1] * bfhi(x.z); a[6] += w1[2] * bflo(x.w); a[7] += w1[3] * bfhi(x.w);
;             }
;             u32x4 o; o.x = pk2(a[0], a[1]); o.y = pk2(a[2], a[3]); o.z = pk2(a[4], a[5]); o.w = pk2(a[6], a[7]);
;             *(u32x4*)(xc + t * 264 + c8) = o;
;         }
.LBB0_1681:
	s_ashr_i32 s1, s0, 31
	s_lshr_b32 s14, s1, 25
	s_add_i32 s14, s0, s14
	s_and_b32 s14, s14, 0xffffff80
	s_lshl_b32 s40, s0, 7
	s_sub_i32 s30, s0, s14
	s_and_saveexec_b64 s[14:15], s[2:3]
	s_cbranch_execz .LBB0_1692
	s_lshl_b32 s26, s30, 7
	s_sub_i32 s31, 0, s26
	s_add_i32 s41, s40, -1
	s_mov_b64 s[26:27], 0
	v_and_b32_e32 v174, 0xf8, v153
	v_lshlrev_b32_e32 v232, 1, v174
	v_mov_b32_e32 v233, 0
	v_lshlrev_b32_e32 v174, 2, v174
	global_load_dwordx4 v[0:3], v174, s[94:95] offset:2048
	global_load_dwordx4 v[4:7], v174, s[94:95] offset:2064
	global_load_dwordx4 v[8:11], v174, s[24:25]
	global_load_dwordx4 v[12:15], v174, s[24:25] offset:16
	global_load_dwordx4 v[16:19], v174, s[24:25] offset:1024
	global_load_dwordx4 v[20:23], v174, s[24:25] offset:1040
	global_load_dwordx4 v[176:179], v174, s[24:25] offset:2048
	global_load_dwordx4 v[180:183], v174, s[24:25] offset:2064
	global_load_dwordx4 v[184:187], v174, s[24:25] offset:3072
	global_load_dwordx4 v[188:191], v174, s[24:25] offset:3088
	v_ashrrev_i32_e32 v175, 5, v142
	v_add_u32_e32 v250, s40, v175
	v_add_u32_e32 v250, -3, v250
	v_mov_b64_e32 v[24:25], s[52:53]
	v_mad_i64_i32 v[24:25], s[42:43], v250, s37, v[24:25]
	v_lshl_add_u64 v[24:25], v[24:25], 0, v[232:233]
	s_mov_b64 s[98:99], 0x800
	v_lshl_add_u64 v[24:25], v[24:25], 0, s[98:99]
	s_mov_b64 s[98:99], 0x1800
	v_lshl_add_u64 v[26:27], v[24:25], 0, s[98:99]
	s_mov_b64 s[98:99], 0xc000
	v_mul_lo_u32 v234, v175, s36
	v_add3_u32 v234, s34, v234, v232
	global_load_dwordx4 v[192:195], v[24:25], off
	global_load_dwordx4 v[196:199], v[24:25], off offset:3072
	global_load_dwordx4 v[200:203], v[26:27], off
	global_load_dwordx4 v[204:207], v[26:27], off offset:3072
	v_lshl_add_u64 v[24:25], v[24:25], 0, s[98:99]
	v_lshl_add_u64 v[26:27], v[26:27], 0, s[98:99]
	global_load_dwordx4 v[208:211], v[24:25], off
	global_load_dwordx4 v[212:215], v[24:25], off offset:3072
	global_load_dwordx4 v[216:219], v[26:27], off
	global_load_dwordx4 v[220:223], v[26:27], off offset:3072
	v_lshl_add_u64 v[24:25], v[24:25], 0, s[98:99]
	v_lshl_add_u64 v[26:27], v[26:27], 0, s[98:99]
	s_waitcnt vmcnt(4)
	v_add_u32_e32 v28, -3, v175
	v_cmp_le_i32_e32 vcc, s31, v28
	s_nop 1
	v_cndmask_b32_e32 v192, 0, v192, vcc
	v_cndmask_b32_e32 v193, 0, v193, vcc
	v_cndmask_b32_e32 v194, 0, v194, vcc
	v_cndmask_b32_e32 v195, 0, v195, vcc
	v_add_u32_e32 v28, -2, v175
	v_cmp_le_i32_e32 vcc, s31, v28
	s_nop 1
	v_cndmask_b32_e32 v196, 0, v196, vcc
	v_cndmask_b32_e32 v197, 0, v197, vcc
	v_cndmask_b32_e32 v198, 0, v198, vcc
	v_cndmask_b32_e32 v199, 0, v199, vcc
	v_add_u32_e32 v28, -1, v175
	v_cmp_le_i32_e32 vcc, s31, v28
	s_nop 1
	v_cndmask_b32_e32 v200, 0, v200, vcc
	v_cndmask_b32_e32 v201, 0, v201, vcc
	v_cndmask_b32_e32 v202, 0, v202, vcc
	v_cndmask_b32_e32 v203, 0, v203, vcc
	v_mov_b64_e32 v[224:225], v[0:1]
	v_mov_b64_e32 v[226:227], v[2:3]
	v_mov_b64_e32 v[228:229], v[4:5]
	v_mov_b64_e32 v[230:231], v[6:7]
	v_lshlrev_b32_e32 v28, 16, v192
	v_and_b32_e32 v29, 0xffff0000, v192
	v_pk_fma_f32 v[224:225], v[8:9], v[28:29], v[224:225]
	v_lshlrev_b32_e32 v28, 16, v193
	v_and_b32_e32 v29, 0xffff0000, v193
	v_pk_fma_f32 v[226:227], v[10:11], v[28:29], v[226:227]
	v_lshlrev_b32_e32 v28, 16, v194
	v_and_b32_e32 v29, 0xffff0000, v194
	v_pk_fma_f32 v[228:229], v[12:13], v[28:29], v[228:229]
	v_lshlrev_b32_e32 v28, 16, v195
	v_and_b32_e32 v29, 0xffff0000, v195
	v_pk_fma_f32 v[230:231], v[14:15], v[28:29], v[230:231]
	v_lshlrev_b32_e32 v28, 16, v196
	v_and_b32_e32 v29, 0xffff0000, v196
	v_pk_fma_f32 v[224:225], v[16:17], v[28:29], v[224:225]
	v_lshlrev_b32_e32 v28, 16, v197
	v_and_b32_e32 v29, 0xffff0000, v197
	v_pk_fma_f32 v[226:227], v[18:19], v[28:29], v[226:227]
	v_lshlrev_b32_e32 v28, 16, v198
	v_and_b32_e32 v29, 0xffff0000, v198
	v_pk_fma_f32 v[228:229], v[20:21], v[28:29], v[228:229]
	v_lshlrev_b32_e32 v28, 16, v199
	v_and_b32_e32 v29, 0xffff0000, v199
	v_pk_fma_f32 v[230:231], v[22:23], v[28:29], v[230:231]
	v_lshlrev_b32_e32 v28, 16, v200
	v_and_b32_e32 v29, 0xffff0000, v200
	v_pk_fma_f32 v[224:225], v[176:177], v[28:29], v[224:225]
	v_lshlrev_b32_e32 v28, 16, v201
	v_and_b32_e32 v29, 0xffff0000, v201
	v_pk_fma_f32 v[226:227], v[178:179], v[28:29], v[226:227]
	v_lshlrev_b32_e32 v28, 16, v202
	v_and_b32_e32 v29, 0xffff0000, v202
	v_pk_fma_f32 v[228:229], v[180:181], v[28:29], v[228:229]
	v_lshlrev_b32_e32 v28, 16, v203
	v_and_b32_e32 v29, 0xffff0000, v203
	v_pk_fma_f32 v[230:231], v[182:183], v[28:29], v[230:231]
	v_lshlrev_b32_e32 v28, 16, v204
	v_and_b32_e32 v29, 0xffff0000, v204
	v_pk_fma_f32 v[224:225], v[184:185], v[28:29], v[224:225]
	v_lshlrev_b32_e32 v28, 16, v205
	v_and_b32_e32 v29, 0xffff0000, v205
	v_pk_fma_f32 v[226:227], v[186:187], v[28:29], v[226:227]
	v_lshlrev_b32_e32 v28, 16, v206
	v_and_b32_e32 v29, 0xffff0000, v206
	v_pk_fma_f32 v[228:229], v[188:189], v[28:29], v[228:229]
	v_lshlrev_b32_e32 v28, 16, v207
	v_and_b32_e32 v29, 0xffff0000, v207
	v_pk_fma_f32 v[230:231], v[190:191], v[28:29], v[230:231]
	v_cvt_pk_bf16_f32 v224, v224, v225
	v_cvt_pk_bf16_f32 v225, v226, v227
	v_cvt_pk_bf16_f32 v226, v228, v229
	v_cvt_pk_bf16_f32 v227, v230, v231
	ds_write_b128 v234, v[224:227]
	s_waitcnt vmcnt(0)
	s_waitcnt lgkmcnt(0)
; DEVI unsigned pk2(float lo, float hi) { unsigned r; asm("v_cvt_pk_bf16_f32 %0, %1, %2" : "=v"(r) : "v"(lo), "v"(hi)); return r; }
; DEVI float bflo(unsigned w) { return __uint_as_float(w << 16); }
; DEVI float bfhi(unsigned w) { return __uint_as_float(w & 0xffff0000u); }
; DEVI void phase_m1(const Params& p, int l, unsigned char* smem) {
;     ...
;         for (int it = tid; it < 128 * 32; it += 512) {
;             const int t = it >> 5, c8 = (it & 31) * 8;
;             float a[8];
; #pragma unroll
;             for (int e = 0; e < 8; ++e) a[e] = p.in[15][l * 256 + c8 + e];
; #pragma unroll
;             for (int k = 0; k < 4; ++k) {
;                 const int tt = t - 3 + k;
;                 if (nloc * 128 + tt < 0) continue;
;                 const u32x4 x = *(const u32x4*)(proj + (size_t)(row0 + tt) * DIN + 1024 + c8);
;                 const f32x4 w0 = *(const f32x4*)(p.in[14] + ((size_t)l * 4 + k) * 256 + c8), w1 = *(const f32x4*)(p.in[14] + ((size_t)l * 4 + k) * 256 + c8 + 4);
;                 a[0] += w0[0] * bflo(x.x); a[1] += w0[1] * bfhi(x.x); a[2] += w0[2] * bflo(x.y); a[3] += w0[3] * bfhi(x.y);
;                 a[4] += w1[0] * bflo(x.z); a[5] += w1[1] * bfhi(x.z); a[6] += w1[2] * bflo(x.w); a[7] += w1[3] * bfhi(x.w);
;             }
;             u32x4 o; o.x = pk2(a[0], a[1]); o.y = pk2(a[2], a[3]); o.z = pk2(a[4], a[5]); o.w = pk2(a[6], a[7]);
;             *(u32x4*)(xc + t * 264 + c8) = o;
;         }
	v_mov_b64_e32 v[224:225], v[0:1]
	v_mov_b64_e32 v[226:227], v[2:3]
	v_mov_b64_e32 v[228:229], v[4:5]
	v_mov_b64_e32 v[230:231], v[6:7]
	v_lshlrev_b32_e32 v28, 16, v208
	v_and_b32_e32 v29, 0xffff0000, v208
	v_pk_fma_f32 v[224:225], v[8:9], v[28:29], v[224:225]
	v_lshlrev_b32_e32 v28, 16, v209
	v_and_b32_e32 v29, 0xffff0000, v209
	v_pk_fma_f32 v[226:227], v[10:11], v[28:29], v[226:227]
	v_lshlrev_b32_e32 v28, 16, v210
	v_and_b32_e32 v29, 0xffff0000, v210
	v_pk_fma_f32 v[228:229], v[12:13], v[28:29], v[228:229]
	v_lshlrev_b32_e32 v28, 16, v211
	v_and_b32_e32 v29, 0xffff0000, v211
	v_pk_fma_f32 v[230:231], v[14:15], v[28:29], v[230:231]
	v_lshlrev_b32_e32 v28, 16, v212
	v_and_b32_e32 v29, 0xffff0000, v212
	v_pk_fma_f32 v[224:225], v[16:17], v[28:29], v[224:225]
	v_lshlrev_b32_e32 v28, 16, v213
	v_and_b32_e32 v29, 0xffff0000, v213
	v_pk_fma_f32 v[226:227], v[18:19], v[28:29], v[226:227]
	v_lshlrev_b32_e32 v28, 16, v214
	v_and_b32_e32 v29, 0xffff0000, v214
	v_pk_fma_f32 v[228:229], v[20:21], v[28:29], v[228:229]
	v_lshlrev_b32_e32 v28, 16, v215
	v_and_b32_e32 v29, 0xffff0000, v215
	v_pk_fma_f32 v[230:231], v[22:23], v[28:29], v[230:231]
	v_lshlrev_b32_e32 v28, 16, v216
	v_and_b32_e32 v29, 0xffff0000, v216
	v_pk_fma_f32 v[224:225], v[176:177], v[28:29], v[224:225]
	v_lshlrev_b32_e32 v28, 16, v217
	v_and_b32_e32 v29, 0xffff0000, v217
	v_pk_fma_f32 v[226:227], v[178:179], v[28:29], v[226:227]
	v_lshlrev_b32_e32 v28, 16, v218
	v_and_b32_e32 v29, 0xffff0000, v218
	v_pk_fma_f32 v[228:229], v[180:181], v[28:29], v[228:229]
	v_lshlrev_b32_e32 v28, 16, v219
	v_and_b32_e32 v29, 0xffff0000, v219
	v_pk_fma_f32 v[230:231], v[182:183], v[28:29], v[230:231]
	v_lshlrev_b32_e32 v28, 16, v220
	v_and_b32_e32 v29, 0xffff0000, v220
	v_pk_fma_f32 v[224:225], v[184:185], v[28:29], v[224:225]
	v_lshlrev_b32_e32 v28, 16, v221
	v_and_b32_e32 v29, 0xffff0000, v221
	v_pk_fma_f32 v[226:227], v[186:187], v[28:29], v[226:227]
	v_lshlrev_b32_e32 v28, 16, v222
	v_and_b32_e32 v29, 0xffff0000, v222
	v_pk_fma_f32 v[228:229], v[188:189], v[28:29], v[228:229]
	v_lshlrev_b32_e32 v28, 16, v223
	v_and_b32_e32 v29, 0xffff0000, v223
	v_pk_fma_f32 v[230:231], v[190:191], v[28:29], v[230:231]
	v_cvt_pk_bf16_f32 v224, v224, v225
	v_cvt_pk_bf16_f32 v225, v226, v227
	v_cvt_pk_bf16_f32 v226, v228, v229
	v_cvt_pk_bf16_f32 v227, v230, v231
	ds_write_b128 v234, v[224:227] offset:8448
	global_load_dwordx4 v[192:195], v[24:25], off
	global_load_dwordx4 v[196:199], v[24:25], off offset:3072
	global_load_dwordx4 v[200:203], v[26:27], off
	global_load_dwordx4 v[204:207], v[26:27], off offset:3072
	v_lshl_add_u64 v[24:25], v[24:25], 0, s[98:99]
	v_lshl_add_u64 v[26:27], v[26:27], 0, s[98:99]
	global_load_dwordx4 v[208:211], v[24:25], off
	global_load_dwordx4 v[212:215], v[24:25], off offset:3072
	global_load_dwordx4 v[216:219], v[26:27], off
	global_load_dwordx4 v[220:223], v[26:27], off offset:3072
	v_lshl_add_u64 v[24:25], v[24:25], 0, s[98:99]
	v_lshl_add_u64 v[26:27], v[26:27], 0, s[98:99]
	s_waitcnt vmcnt(4)
	s_waitcnt lgkmcnt(0)
	v_mov_b64_e32 v[224:225], v[0:1]
	v_mov_b64_e32 v[226:227], v[2:3]
	v_mov_b64_e32 v[228:229], v[4:5]
	v_mov_b64_e32 v[230:231], v[6:7]
	v_lshlrev_b32_e32 v28, 16, v192
	v_and_b32_e32 v29, 0xffff0000, v192
	v_pk_fma_f32 v[224:225], v[8:9], v[28:29], v[224:225]
	v_lshlrev_b32_e32 v28, 16, v193
	v_and_b32_e32 v29, 0xffff0000, v193
	v_pk_fma_f32 v[226:227], v[10:11], v[28:29], v[226:227]
	v_lshlrev_b32_e32 v28, 16, v194
	v_and_b32_e32 v29, 0xffff0000, v194
	v_pk_fma_f32 v[228:229], v[12:13], v[28:29], v[228:229]
	v_lshlrev_b32_e32 v28, 16, v195
	v_and_b32_e32 v29, 0xffff0000, v195
	v_pk_fma_f32 v[230:231], v[14:15], v[28:29], v[230:231]
	v_lshlrev_b32_e32 v28, 16, v196
	v_and_b32_e32 v29, 0xffff0000, v196
	v_pk_fma_f32 v[224:225], v[16:17], v[28:29], v[224:225]
	v_lshlrev_b32_e32 v28, 16, v197
	v_and_b32_e32 v29, 0xffff0000, v197
	v_pk_fma_f32 v[226:227], v[18:19], v[28:29], v[226:227]
	v_lshlrev_b32_e32 v28, 16, v198
	v_and_b32_e32 v29, 0xffff0000, v198
	v_pk_fma_f32 v[228:229], v[20:21], v[28:29], v[228:229]
	v_lshlrev_b32_e32 v28, 16, v199
	v_and_b32_e32 v29, 0xffff0000, v199
	v_pk_fma_f32 v[230:231], v[22:23], v[28:29], v[230:231]
	v_lshlrev_b32_e32 v28, 16, v200
	v_and_b32_e32 v29, 0xffff0000, v200
	v_pk_fma_f32 v[224:225], v[176:177], v[28:29], v[224:225]
	v_lshlrev_b32_e32 v28, 16, v201
	v_and_b32_e32 v29, 0xffff0000, v201
	v_pk_fma_f32 v[226:227], v[178:179], v[28:29], v[226:227]
	v_lshlrev_b32_e32 v28, 16, v202
	v_and_b32_e32 v29, 0xffff0000, v202
	v_pk_fma_f32 v[228:229], v[180:181], v[28:29], v[228:229]
	v_lshlrev_b32_e32 v28, 16, v203
	v_and_b32_e32 v29, 0xffff0000, v203
	v_pk_fma_f32 v[230:231], v[182:183], v[28:29], v[230:231]
	v_lshlrev_b32_e32 v28, 16, v204
	v_and_b32_e32 v29, 0xffff0000, v204
	v_pk_fma_f32 v[224:225], v[184:185], v[28:29], v[224:225]
	v_lshlrev_b32_e32 v28, 16, v205
	v_and_b32_e32 v29, 0xffff0000, v205
	v_pk_fma_f32 v[226:227], v[186:187], v[28:29], v[226:227]
	v_lshlrev_b32_e32 v28, 16, v206
	v_and_b32_e32 v29, 0xffff0000, v206
	v_pk_fma_f32 v[228:229], v[188:189], v[28:29], v[228:229]
	v_lshlrev_b32_e32 v28, 16, v207
	v_and_b32_e32 v29, 0xffff0000, v207
	v_pk_fma_f32 v[230:231], v[190:191], v[28:29], v[230:231]
	v_cvt_pk_bf16_f32 v224, v224, v225
	v_cvt_pk_bf16_f32 v225, v226, v227
	v_cvt_pk_bf16_f32 v226, v228, v229
	v_cvt_pk_bf16_f32 v227, v230, v231
	ds_write_b128 v234, v[224:227] offset:16896
	s_waitcnt vmcnt(0)
	s_waitcnt lgkmcnt(0)
; DEVI unsigned pk2(float lo, float hi) { unsigned r; asm("v_cvt_pk_bf16_f32 %0, %1, %2" : "=v"(r) : "v"(lo), "v"(hi)); return r; }
; DEVI float bflo(unsigned w) { return __uint_as_float(w << 16); }
; DEVI float bfhi(unsigned w) { return __uint_as_float(w & 0xffff0000u); }
; DEVI void phase_m1(const Params& p, int l, unsigned char* smem) {
;     ...
;         for (int it = tid; it < 128 * 32; it += 512) {
;             const int t = it >> 5, c8 = (it & 31) * 8;
;             float a[8];
; #pragma unroll
;             for (int e = 0; e < 8; ++e) a[e] = p.in[15][l * 256 + c8 + e];
; #pragma unroll
;             for (int k = 0; k < 4; ++k) {
;                 const int tt = t - 3 + k;
;                 if (nloc * 128 + tt < 0) continue;
;                 const u32x4 x = *(const u32x4*)(proj + (size_t)(row0 + tt) * DIN + 1024 + c8);
;                 const f32x4 w0 = *(const f32x4*)(p.in[14] + ((size_t)l * 4 + k) * 256 + c8), w1 = *(const f32x4*)(p.in[14] + ((size_t)l * 4 + k) * 256 + c8 + 4);
;                 a[0] += w0[0] * bflo(x.x); a[1] += w0[1] * bfhi(x.x); a[2] += w0[2] * bflo(x.y); a[3] += w0[3] * bfhi(x.y);
;                 a[4] += w1[0] * bflo(x.z); a[5] += w1[1] * bfhi(x.z); a[6] += w1[2] * bflo(x.w); a[7] += w1[3] * bfhi(x.w);
;             }
;             u32x4 o; o.x = pk2(a[0], a[1]); o.y = pk2(a[2], a[3]); o.z = pk2(a[4], a[5]); o.w = pk2(a[6], a[7]);
;             *(u32x4*)(xc + t * 264 + c8) = o;
;         }
	v_mov_b64_e32 v[224:225], v[0:1]
	v_mov_b64_e32 v[226:227], v[2:3]
	v_mov_b64_e32 v[228:229], v[4:5]
	v_mov_b64_e32 v[230:231], v[6:7]
	v_lshlrev_b32_e32 v28, 16, v208
	v_and_b32_e32 v29, 0xffff0000, v208
	v_pk_fma_f32 v[224:225], v[8:9], v[28:29], v[224:225]
	v_lshlrev_b32_e32 v28, 16, v209
	v_and_b32_e32 v29, 0xffff0000, v209
	v_pk_fma_f32 v[226:227], v[10:11], v[28:29], v[226:227]
	v_lshlrev_b32_e32 v28, 16, v210
	v_and_b32_e32 v29, 0xffff0000, v210
	v_pk_fma_f32 v[228:229], v[12:13], v[28:29], v[228:229]
	v_lshlrev_b32_e32 v28, 16, v211
	v_and_b32_e32 v29, 0xffff0000, v211
	v_pk_fma_f32 v[230:231], v[14:15], v[28:29], v[230:231]
	v_lshlrev_b32_e32 v28, 16, v212
	v_and_b32_e32 v29, 0xffff0000, v212
	v_pk_fma_f32 v[224:225], v[16:17], v[28:29], v[224:225]
	v_lshlrev_b32_e32 v28, 16, v213
	v_and_b32_e32 v29, 0xffff0000, v213
	v_pk_fma_f32 v[226:227], v[18:19], v[28:29], v[226:227]
	v_lshlrev_b32_e32 v28, 16, v214
	v_and_b32_e32 v29, 0xffff0000, v214
	v_pk_fma_f32 v[228:229], v[20:21], v[28:29], v[228:229]
	v_lshlrev_b32_e32 v28, 16, v215
	v_and_b32_e32 v29, 0xffff0000, v215
	v_pk_fma_f32 v[230:231], v[22:23], v[28:29], v[230:231]
	v_lshlrev_b32_e32 v28, 16, v216
	v_and_b32_e32 v29, 0xffff0000, v216
	v_pk_fma_f32 v[224:225], v[176:177], v[28:29], v[224:225]
	v_lshlrev_b32_e32 v28, 16, v217
	v_and_b32_e32 v29, 0xffff0000, v217
	v_pk_fma_f32 v[226:227], v[178:179], v[28:29], v[226:227]
	v_lshlrev_b32_e32 v28, 16, v218
	v_and_b32_e32 v29, 0xffff0000, v218
	v_pk_fma_f32 v[228:229], v[180:181], v[28:29], v[228:229]
	v_lshlrev_b32_e32 v28, 16, v219
	v_and_b32_e32 v29, 0xffff0000, v219
	v_pk_fma_f32 v[230:231], v[182:183], v[28:29], v[230:231]
	v_lshlrev_b32_e32 v28, 16, v220
	v_and_b32_e32 v29, 0xffff0000, v220
	v_pk_fma_f32 v[224:225], v[184:185], v[28:29], v[224:225]
	v_lshlrev_b32_e32 v28, 16, v221
	v_and_b32_e32 v29, 0xffff0000, v221
	v_pk_fma_f32 v[226:227], v[186:187], v[28:29], v[226:227]
	v_lshlrev_b32_e32 v28, 16, v222
	v_and_b32_e32 v29, 0xffff0000, v222
	v_pk_fma_f32 v[228:229], v[188:189], v[28:29], v[228:229]
	v_lshlrev_b32_e32 v28, 16, v223
	v_and_b32_e32 v29, 0xffff0000, v223
	v_pk_fma_f32 v[230:231], v[190:191], v[28:29], v[230:231]
	v_cvt_pk_bf16_f32 v224, v224, v225
	v_cvt_pk_bf16_f32 v225, v226, v227
	v_cvt_pk_bf16_f32 v226, v228, v229
	v_cvt_pk_bf16_f32 v227, v230, v231
	ds_write_b128 v234, v[224:227] offset:25344
	global_load_dwordx4 v[192:195], v[24:25], off
	global_load_dwordx4 v[196:199], v[24:25], off offset:3072
	global_load_dwordx4 v[200:203], v[26:27], off
	global_load_dwordx4 v[204:207], v[26:27], off offset:3072
	v_lshl_add_u64 v[24:25], v[24:25], 0, s[98:99]
	v_lshl_add_u64 v[26:27], v[26:27], 0, s[98:99]
	global_load_dwordx4 v[208:211], v[24:25], off
	global_load_dwordx4 v[212:215], v[24:25], off offset:3072
	global_load_dwordx4 v[216:219], v[26:27], off
	global_load_dwordx4 v[220:223], v[26:27], off offset:3072
	v_lshl_add_u64 v[24:25], v[24:25], 0, s[98:99]
	v_lshl_add_u64 v[26:27], v[26:27], 0, s[98:99]
	s_waitcnt vmcnt(4)
	s_waitcnt lgkmcnt(0)
	v_mov_b64_e32 v[224:225], v[0:1]
	v_mov_b64_e32 v[226:227], v[2:3]
	v_mov_b64_e32 v[228:229], v[4:5]
	v_mov_b64_e32 v[230:231], v[6:7]
	v_lshlrev_b32_e32 v28, 16, v192
	v_and_b32_e32 v29, 0xffff0000, v192
	v_pk_fma_f32 v[224:225], v[8:9], v[28:29], v[224:225]
	v_lshlrev_b32_e32 v28, 16, v193
	v_and_b32_e32 v29, 0xffff0000, v193
	v_pk_fma_f32 v[226:227], v[10:11], v[28:29], v[226:227]
	v_lshlrev_b32_e32 v28, 16, v194
	v_and_b32_e32 v29, 0xffff0000, v194
	v_pk_fma_f32 v[228:229], v[12:13], v[28:29], v[228:229]
	v_lshlrev_b32_e32 v28, 16, v195
	v_and_b32_e32 v29, 0xffff0000, v195
	v_pk_fma_f32 v[230:231], v[14:15], v[28:29], v[230:231]
	v_lshlrev_b32_e32 v28, 16, v196
	v_and_b32_e32 v29, 0xffff0000, v196
	v_pk_fma_f32 v[224:225], v[16:17], v[28:29], v[224:225]
	v_lshlrev_b32_e32 v28, 16, v197
	v_and_b32_e32 v29, 0xffff0000, v197
	v_pk_fma_f32 v[226:227], v[18:19], v[28:29], v[226:227]
	v_lshlrev_b32_e32 v28, 16, v198
	v_and_b32_e32 v29, 0xffff0000, v198
	v_pk_fma_f32 v[228:229], v[20:21], v[28:29], v[228:229]
	v_lshlrev_b32_e32 v28, 16, v199
	v_and_b32_e32 v29, 0xffff0000, v199
	v_pk_fma_f32 v[230:231], v[22:23], v[28:29], v[230:231]
	v_lshlrev_b32_e32 v28, 16, v200
	v_and_b32_e32 v29, 0xffff0000, v200
	v_pk_fma_f32 v[224:225], v[176:177], v[28:29], v[224:225]
	v_lshlrev_b32_e32 v28, 16, v201
	v_and_b32_e32 v29, 0xffff0000, v201
	v_pk_fma_f32 v[226:227], v[178:179], v[28:29], v[226:227]
	v_lshlrev_b32_e32 v28, 16, v202
	v_and_b32_e32 v29, 0xffff0000, v202
	v_pk_fma_f32 v[228:229], v[180:181], v[28:29], v[228:229]
	v_lshlrev_b32_e32 v28, 16, v203
	v_and_b32_e32 v29, 0xffff0000, v203
	v_pk_fma_f32 v[230:231], v[182:183], v[28:29], v[230:231]
	v_lshlrev_b32_e32 v28, 16, v204
	v_and_b32_e32 v29, 0xffff0000, v204
	v_pk_fma_f32 v[224:225], v[184:185], v[28:29], v[224:225]
	v_lshlrev_b32_e32 v28, 16, v205
	v_and_b32_e32 v29, 0xffff0000, v205
	v_pk_fma_f32 v[226:227], v[186:187], v[28:29], v[226:227]
	v_lshlrev_b32_e32 v28, 16, v206
	v_and_b32_e32 v29, 0xffff0000, v206
	v_pk_fma_f32 v[228:229], v[188:189], v[28:29], v[228:229]
	v_lshlrev_b32_e32 v28, 16, v207
	v_and_b32_e32 v29, 0xffff0000, v207
	v_pk_fma_f32 v[230:231], v[190:191], v[28:29], v[230:231]
	v_cvt_pk_bf16_f32 v224, v224, v225
	v_cvt_pk_bf16_f32 v225, v226, v227
	v_cvt_pk_bf16_f32 v226, v228, v229
	v_cvt_pk_bf16_f32 v227, v230, v231
	ds_write_b128 v234, v[224:227] offset:33792
	s_waitcnt vmcnt(0)
	s_waitcnt lgkmcnt(0)
; DEVI unsigned pk2(float lo, float hi) { unsigned r; asm("v_cvt_pk_bf16_f32 %0, %1, %2" : "=v"(r) : "v"(lo), "v"(hi)); return r; }
; DEVI float bflo(unsigned w) { return __uint_as_float(w << 16); }
; DEVI float bfhi(unsigned w) { return __uint_as_float(w & 0xffff0000u); }
; DEVI void phase_m1(const Params& p, int l, unsigned char* smem) {
;     ...
;         for (int it = tid; it < 128 * 32; it += 512) {
;             const int t = it >> 5, c8 = (it & 31) * 8;
;             float a[8];
; #pragma unroll
;             for (int e = 0; e < 8; ++e) a[e] = p.in[15][l * 256 + c8 + e];
; #pragma unroll
;             for (int k = 0; k < 4; ++k) {
;                 const int tt = t - 3 + k;
;                 if (nloc * 128 + tt < 0) continue;
;                 const u32x4 x = *(const u32x4*)(proj + (size_t)(row0 + tt) * DIN + 1024 + c8);
;                 const f32x4 w0 = *(const f32x4*)(p.in[14] + ((size_t)l * 4 + k) * 256 + c8), w1 = *(const f32x4*)(p.in[14] + ((size_t)l * 4 + k) * 256 + c8 + 4);
;                 a[0] += w0[0] * bflo(x.x); a[1] += w0[1] * bfhi(x.x); a[2] += w0[2] * bflo(x.y); a[3] += w0[3] * bfhi(x.y);
;                 a[4] += w1[0] * bflo(x.z); a[5] += w1[1] * bfhi(x.z); a[6] += w1[2] * bflo(x.w); a[7] += w1[3] * bfhi(x.w);
;             }
;             u32x4 o; o.x = pk2(a[0], a[1]); o.y = pk2(a[2], a[3]); o.z = pk2(a[4], a[5]); o.w = pk2(a[6], a[7]);
;             *(u32x4*)(xc + t * 264 + c8) = o;
;         }
	v_mov_b64_e32 v[224:225], v[0:1]
	v_mov_b64_e32 v[226:227], v[2:3]
	v_mov_b64_e32 v[228:229], v[4:5]
	v_mov_b64_e32 v[230:231], v[6:7]
	v_lshlrev_b32_e32 v28, 16, v208
	v_and_b32_e32 v29, 0xffff0000, v208
	v_pk_fma_f32 v[224:225], v[8:9], v[28:29], v[224:225]
	v_lshlrev_b32_e32 v28, 16, v209
	v_and_b32_e32 v29, 0xffff0000, v209
	v_pk_fma_f32 v[226:227], v[10:11], v[28:29], v[226:227]
	v_lshlrev_b32_e32 v28, 16, v210
	v_and_b32_e32 v29, 0xffff0000, v210
	v_pk_fma_f32 v[228:229], v[12:13], v[28:29], v[228:229]
	v_lshlrev_b32_e32 v28, 16, v211
	v_and_b32_e32 v29, 0xffff0000, v211
	v_pk_fma_f32 v[230:231], v[14:15], v[28:29], v[230:231]
	v_lshlrev_b32_e32 v28, 16, v212
	v_and_b32_e32 v29, 0xffff0000, v212
	v_pk_fma_f32 v[224:225], v[16:17], v[28:29], v[224:225]
	v_lshlrev_b32_e32 v28, 16, v213
	v_and_b32_e32 v29, 0xffff0000, v213
	v_pk_fma_f32 v[226:227], v[18:19], v[28:29], v[226:227]
	v_lshlrev_b32_e32 v28, 16, v214
	v_and_b32_e32 v29, 0xffff0000, v214
	v_pk_fma_f32 v[228:229], v[20:21], v[28:29], v[228:229]
	v_lshlrev_b32_e32 v28, 16, v215
	v_and_b32_e32 v29, 0xffff0000, v215
	v_pk_fma_f32 v[230:231], v[22:23], v[28:29], v[230:231]
	v_lshlrev_b32_e32 v28, 16, v216
	v_and_b32_e32 v29, 0xffff0000, v216
	v_pk_fma_f32 v[224:225], v[176:177], v[28:29], v[224:225]
	v_lshlrev_b32_e32 v28, 16, v217
	v_and_b32_e32 v29, 0xffff0000, v217
	v_pk_fma_f32 v[226:227], v[178:179], v[28:29], v[226:227]
	v_lshlrev_b32_e32 v28, 16, v218
	v_and_b32_e32 v29, 0xffff0000, v218
	v_pk_fma_f32 v[228:229], v[180:181], v[28:29], v[228:229]
	v_lshlrev_b32_e32 v28, 16, v219
	v_and_b32_e32 v29, 0xffff0000, v219
	v_pk_fma_f32 v[230:231], v[182:183], v[28:29], v[230:231]
	v_lshlrev_b32_e32 v28, 16, v220
	v_and_b32_e32 v29, 0xffff0000, v220
	v_pk_fma_f32 v[224:225], v[184:185], v[28:29], v[224:225]
	v_lshlrev_b32_e32 v28, 16, v221
	v_and_b32_e32 v29, 0xffff0000, v221
	v_pk_fma_f32 v[226:227], v[186:187], v[28:29], v[226:227]
	v_lshlrev_b32_e32 v28, 16, v222
	v_and_b32_e32 v29, 0xffff0000, v222
	v_pk_fma_f32 v[228:229], v[188:189], v[28:29], v[228:229]
	v_lshlrev_b32_e32 v28, 16, v223
	v_and_b32_e32 v29, 0xffff0000, v223
	v_pk_fma_f32 v[230:231], v[190:191], v[28:29], v[230:231]
	v_cvt_pk_bf16_f32 v224, v224, v225
	v_cvt_pk_bf16_f32 v225, v226, v227
	v_cvt_pk_bf16_f32 v226, v228, v229
	v_cvt_pk_bf16_f32 v227, v230, v231
	ds_write_b128 v234, v[224:227] offset:42240
	global_load_dwordx4 v[192:195], v[24:25], off
	global_load_dwordx4 v[196:199], v[24:25], off offset:3072
	global_load_dwordx4 v[200:203], v[26:27], off
	global_load_dwordx4 v[204:207], v[26:27], off offset:3072
	v_lshl_add_u64 v[24:25], v[24:25], 0, s[98:99]
	v_lshl_add_u64 v[26:27], v[26:27], 0, s[98:99]
	global_load_dwordx4 v[208:211], v[24:25], off
	global_load_dwordx4 v[212:215], v[24:25], off offset:3072
	global_load_dwordx4 v[216:219], v[26:27], off
	global_load_dwordx4 v[220:223], v[26:27], off offset:3072
	v_lshl_add_u64 v[24:25], v[24:25], 0, s[98:99]
	v_lshl_add_u64 v[26:27], v[26:27], 0, s[98:99]
	s_waitcnt vmcnt(4)
	s_waitcnt lgkmcnt(0)
; DEVI unsigned pk2(float lo, float hi) { unsigned r; asm("v_cvt_pk_bf16_f32 %0, %1, %2" : "=v"(r) : "v"(lo), "v"(hi)); return r; }
; DEVI float bflo(unsigned w) { return __uint_as_float(w << 16); }
; DEVI float bfhi(unsigned w) { return __uint_as_float(w & 0xffff0000u); }
; DEVI void phase_m1(const Params& p, int l, unsigned char* smem) {
;     ...
;         for (int it = tid; it < 128 * 32; it += 512) {
;             const int t = it >> 5, c8 = (it & 31) * 8;
;             float a[8];
; #pragma unroll
;             for (int e = 0; e < 8; ++e) a[e] = p.in[15][l * 256 + c8 + e];
; #pragma unroll
;             for (int k = 0; k < 4; ++k) {
;                 const int tt = t - 3 + k;
;                 if (nloc * 128 + tt < 0) continue;
;                 const u32x4 x = *(const u32x4*)(proj + (size_t)(row0 + tt) * DIN + 1024 + c8);
;                 const f32x4 w0 = *(const f32x4*)(p.in[14] + ((size_t)l * 4 + k) * 256 + c8), w1 = *(const f32x4*)(p.in[14] + ((size_t)l * 4 + k) * 256 + c8 + 4);
;                 a[0] += w0[0] * bflo(x.x); a[1] += w0[1] * bfhi(x.x); a[2] += w0[2] * bflo(x.y); a[3] += w0[3] * bfhi(x.y);
;                 a[4] += w1[0] * bflo(x.z); a[5] += w1[1] * bfhi(x.z); a[6] += w1[2] * bflo(x.w); a[7] += w1[3] * bfhi(x.w);
;             }
;             u32x4 o; o.x = pk2(a[0], a[1]); o.y = pk2(a[2], a[3]); o.z = pk2(a[4], a[5]); o.w = pk2(a[6], a[7]);
;             *(u32x4*)(xc + t * 264 + c8) = o;
;         }
	v_mov_b64_e32 v[224:225], v[0:1]
	v_mov_b64_e32 v[226:227], v[2:3]
	v_mov_b64_e32 v[228:229], v[4:5]
	v_mov_b64_e32 v[230:231], v[6:7]
	v_lshlrev_b32_e32 v28, 16, v192
	v_and_b32_e32 v29, 0xffff0000, v192
	v_pk_fma_f32 v[224:225], v[8:9], v[28:29], v[224:225]
	v_lshlrev_b32_e32 v28, 16, v193
	v_and_b32_e32 v29, 0xffff0000, v193
	v_pk_fma_f32 v[226:227], v[10:11], v[28:29], v[226:227]
	v_lshlrev_b32_e32 v28, 16, v194
	v_and_b32_e32 v29, 0xffff0000, v194
	v_pk_fma_f32 v[228:229], v[12:13], v[28:29], v[228:229]
	v_lshlrev_b32_e32 v28, 16, v195
	v_and_b32_e32 v29, 0xffff0000, v195
	v_pk_fma_f32 v[230:231], v[14:15], v[28:29], v[230:231]
	v_lshlrev_b32_e32 v28, 16, v196
	v_and_b32_e32 v29, 0xffff0000, v196
	v_pk_fma_f32 v[224:225], v[16:17], v[28:29], v[224:225]
	v_lshlrev_b32_e32 v28, 16, v197
	v_and_b32_e32 v29, 0xffff0000, v197
	v_pk_fma_f32 v[226:227], v[18:19], v[28:29], v[226:227]
	v_lshlrev_b32_e32 v28, 16, v198
	v_and_b32_e32 v29, 0xffff0000, v198
	v_pk_fma_f32 v[228:229], v[20:21], v[28:29], v[228:229]
	v_lshlrev_b32_e32 v28, 16, v199
	v_and_b32_e32 v29, 0xffff0000, v199
	v_pk_fma_f32 v[230:231], v[22:23], v[28:29], v[230:231]
	v_lshlrev_b32_e32 v28, 16, v200
	v_and_b32_e32 v29, 0xffff0000, v200
	v_pk_fma_f32 v[224:225], v[176:177], v[28:29], v[224:225]
	v_lshlrev_b32_e32 v28, 16, v201
	v_and_b32_e32 v29, 0xffff0000, v201
	v_pk_fma_f32 v[226:227], v[178:179], v[28:29], v[226:227]
	v_lshlrev_b32_e32 v28, 16, v202
	v_and_b32_e32 v29, 0xffff0000, v202
	v_pk_fma_f32 v[228:229], v[180:181], v[28:29], v[228:229]
	v_lshlrev_b32_e32 v28, 16, v203
	v_and_b32_e32 v29, 0xffff0000, v203
	v_pk_fma_f32 v[230:231], v[182:183], v[28:29], v[230:231]
	v_lshlrev_b32_e32 v28, 16, v204
	v_and_b32_e32 v29, 0xffff0000, v204
	v_pk_fma_f32 v[224:225], v[184:185], v[28:29], v[224:225]
	v_lshlrev_b32_e32 v28, 16, v205
	v_and_b32_e32 v29, 0xffff0000, v205
	v_pk_fma_f32 v[226:227], v[186:187], v[28:29], v[226:227]
	v_lshlrev_b32_e32 v28, 16, v206
	v_and_b32_e32 v29, 0xffff0000, v206
	v_pk_fma_f32 v[228:229], v[188:189], v[28:29], v[228:229]
	v_lshlrev_b32_e32 v28, 16, v207
	v_and_b32_e32 v29, 0xffff0000, v207
	v_pk_fma_f32 v[230:231], v[190:191], v[28:29], v[230:231]
	v_cvt_pk_bf16_f32 v224, v224, v225
	v_cvt_pk_bf16_f32 v225, v226, v227
	v_cvt_pk_bf16_f32 v226, v228, v229
	v_cvt_pk_bf16_f32 v227, v230, v231
	ds_write_b128 v234, v[224:227] offset:50688
	s_waitcnt vmcnt(0)
	s_waitcnt lgkmcnt(0)
	v_mov_b64_e32 v[224:225], v[0:1]
	v_mov_b64_e32 v[226:227], v[2:3]
	v_mov_b64_e32 v[228:229], v[4:5]
	v_mov_b64_e32 v[230:231], v[6:7]
	v_lshlrev_b32_e32 v28, 16, v208
	v_and_b32_e32 v29, 0xffff0000, v208
	v_pk_fma_f32 v[224:225], v[8:9], v[28:29], v[224:225]
	v_lshlrev_b32_e32 v28, 16, v209
	v_and_b32_e32 v29, 0xffff0000, v209
	v_pk_fma_f32 v[226:227], v[10:11], v[28:29], v[226:227]
	v_lshlrev_b32_e32 v28, 16, v210
	v_and_b32_e32 v29, 0xffff0000, v210
	v_pk_fma_f32 v[228:229], v[12:13], v[28:29], v[228:229]
	v_lshlrev_b32_e32 v28, 16, v211
	v_and_b32_e32 v29, 0xffff0000, v211
	v_pk_fma_f32 v[230:231], v[14:15], v[28:29], v[230:231]
	v_lshlrev_b32_e32 v28, 16, v212
	v_and_b32_e32 v29, 0xffff0000, v212
	v_pk_fma_f32 v[224:225], v[16:17], v[28:29], v[224:225]
	v_lshlrev_b32_e32 v28, 16, v213
	v_and_b32_e32 v29, 0xffff0000, v213
	v_pk_fma_f32 v[226:227], v[18:19], v[28:29], v[226:227]
	v_lshlrev_b32_e32 v28, 16, v214
	v_and_b32_e32 v29, 0xffff0000, v214
	v_pk_fma_f32 v[228:229], v[20:21], v[28:29], v[228:229]
	v_lshlrev_b32_e32 v28, 16, v215
	v_and_b32_e32 v29, 0xffff0000, v215
	v_pk_fma_f32 v[230:231], v[22:23], v[28:29], v[230:231]
	v_lshlrev_b32_e32 v28, 16, v216
	v_and_b32_e32 v29, 0xffff0000, v216
	v_pk_fma_f32 v[224:225], v[176:177], v[28:29], v[224:225]
	v_lshlrev_b32_e32 v28, 16, v217
	v_and_b32_e32 v29, 0xffff0000, v217
	v_pk_fma_f32 v[226:227], v[178:179], v[28:29], v[226:227]
	v_lshlrev_b32_e32 v28, 16, v218
	v_and_b32_e32 v29, 0xffff0000, v218
	v_pk_fma_f32 v[228:229], v[180:181], v[28:29], v[228:229]
	v_lshlrev_b32_e32 v28, 16, v219
	v_and_b32_e32 v29, 0xffff0000, v219
	v_pk_fma_f32 v[230:231], v[182:183], v[28:29], v[230:231]
	v_lshlrev_b32_e32 v28, 16, v220
	v_and_b32_e32 v29, 0xffff0000, v220
	v_pk_fma_f32 v[224:225], v[184:185], v[28:29], v[224:225]
	v_lshlrev_b32_e32 v28, 16, v221
	v_and_b32_e32 v29, 0xffff0000, v221
	v_pk_fma_f32 v[226:227], v[186:187], v[28:29], v[226:227]
	v_lshlrev_b32_e32 v28, 16, v222
	v_and_b32_e32 v29, 0xffff0000, v222
	v_pk_fma_f32 v[228:229], v[188:189], v[28:29], v[228:229]
	v_lshlrev_b32_e32 v28, 16, v223
	v_and_b32_e32 v29, 0xffff0000, v223
	v_pk_fma_f32 v[230:231], v[190:191], v[28:29], v[230:231]
	v_cvt_pk_bf16_f32 v224, v224, v225
	v_cvt_pk_bf16_f32 v225, v226, v227
	v_cvt_pk_bf16_f32 v226, v228, v229
	v_cvt_pk_bf16_f32 v227, v230, v231
	ds_write_b128 v234, v[224:227] offset:59136

; DEVI int bid_() { int t = blockIdx.x; asm volatile("" : "+s"(t)); return t; }
; DEVI int gdim_() { int t = gridDim.x; asm volatile("" : "+s"(t)); return t; }
; DEVI unsigned pk2(float lo, float hi) { unsigned r; asm("v_cvt_pk_bf16_f32 %0, %1, %2" : "=v"(r) : "v"(lo), "v"(hi)); return r; }
; DEVI float bflo(unsigned w) { return __uint_as_float(w << 16); }
; DEVI float bfhi(unsigned w) { return __uint_as_float(w & 0xffff0000u); }
; DEVI void phase_m1(const Params& p, int l, unsigned char* smem) {
;     ...
;     for (int tile = bid_(); tile < NTILE; tile += gdim_()) {
;         const int row0 = tile * 128, nloc = tile % TPB;
;         for (int it = tid; it < 128 * 32; it += 512) {
;             const int t = it >> 5, c8 = (it & 31) * 8;
;             float a[8];
; #pragma unroll
;             for (int e = 0; e < 8; ++e) a[e] = p.in[15][l * 256 + c8 + e];
; #pragma unroll
;             for (int k = 0; k < 4; ++k) {
;                 const int tt = t - 3 + k;
;                 if (nloc * 128 + tt < 0) continue;
;                 const u32x4 x = *(const u32x4*)(proj + (size_t)(row0 + tt) * DIN + 1024 + c8);
;                 const f32x4 w0 = *(const f32x4*)(p.in[14] + ((size_t)l * 4 + k) * 256 + c8), w1 = *(const f32x4*)(p.in[14] + ((size_t)l * 4 + k) * 256 + c8 + 4);
;                 a[0] += w0[0] * bflo(x.x); a[1] += w0[1] * bfhi(x.x); a[2] += w0[2] * bflo(x.y); a[3] += w0[3] * bfhi(x.y);
;                 a[4] += w1[0] * bflo(x.z); a[5] += w1[1] * bfhi(x.z); a[6] += w1[2] * bflo(x.w); a[7] += w1[3] * bfhi(x.w);
;             }
;             u32x4 o; o.x = pk2(a[0], a[1]); o.y = pk2(a[2], a[3]); o.z = pk2(a[4], a[5]); o.w = pk2(a[6], a[7]);
;             *(u32x4*)(xc + t * 264 + c8) = o;
;         }
.LBB0_2335:
	s_ashr_i32 s1, s0, 31
	s_lshr_b32 s14, s1, 25
	s_add_i32 s14, s0, s14
	s_and_b32 s14, s14, 0xffffff80
	s_lshl_b32 s40, s0, 7
	s_sub_i32 s30, s0, s14
	s_and_saveexec_b64 s[14:15], s[2:3]
	s_cbranch_execz .LBB0_2346
	s_lshl_b32 s26, s30, 7
	s_sub_i32 s31, 0, s26
	s_add_i32 s41, s40, -1
	s_mov_b64 s[26:27], 0
	v_and_b32_e32 v174, 0xf8, v153
	v_lshlrev_b32_e32 v232, 1, v174
	v_mov_b32_e32 v233, 0
	v_lshlrev_b32_e32 v174, 2, v174
	global_load_dwordx4 v[0:3], v174, s[94:95] offset:3072
	global_load_dwordx4 v[4:7], v174, s[94:95] offset:3088
	global_load_dwordx4 v[8:11], v174, s[24:25]
	global_load_dwordx4 v[12:15], v174, s[24:25] offset:16
	global_load_dwordx4 v[16:19], v174, s[24:25] offset:1024
	global_load_dwordx4 v[20:23], v174, s[24:25] offset:1040
	global_load_dwordx4 v[176:179], v174, s[24:25] offset:2048
	global_load_dwordx4 v[180:183], v174, s[24:25] offset:2064
	global_load_dwordx4 v[184:187], v174, s[24:25] offset:3072
	global_load_dwordx4 v[188:191], v174, s[24:25] offset:3088
	v_ashrrev_i32_e32 v175, 5, v142
	v_add_u32_e32 v250, s40, v175
	v_add_u32_e32 v250, -3, v250
	v_mov_b64_e32 v[24:25], s[52:53]
	v_mad_i64_i32 v[24:25], s[42:43], v250, s37, v[24:25]
	v_lshl_add_u64 v[24:25], v[24:25], 0, v[232:233]
	s_mov_b64 s[98:99], 0x800
	v_lshl_add_u64 v[24:25], v[24:25], 0, s[98:99]
	s_mov_b64 s[98:99], 0x1800
	v_lshl_add_u64 v[26:27], v[24:25], 0, s[98:99]
	s_mov_b64 s[98:99], 0xc000
	v_mul_lo_u32 v234, v175, s36
	v_add3_u32 v234, s34, v234, v232
	global_load_dwordx4 v[192:195], v[24:25], off
	global_load_dwordx4 v[196:199], v[24:25], off offset:3072
	global_load_dwordx4 v[200:203], v[26:27], off
	global_load_dwordx4 v[204:207], v[26:27], off offset:3072
	v_lshl_add_u64 v[24:25], v[24:25], 0, s[98:99]
	v_lshl_add_u64 v[26:27], v[26:27], 0, s[98:99]
	global_load_dwordx4 v[208:211], v[24:25], off
	global_load_dwordx4 v[212:215], v[24:25], off offset:3072
	global_load_dwordx4 v[216:219], v[26:27], off
	global_load_dwordx4 v[220:223], v[26:27], off offset:3072
	v_lshl_add_u64 v[24:25], v[24:25], 0, s[98:99]
	v_lshl_add_u64 v[26:27], v[26:27], 0, s[98:99]
	s_waitcnt vmcnt(4)
	v_add_u32_e32 v28, -3, v175
	v_cmp_le_i32_e32 vcc, s31, v28
	s_nop 1
	v_cndmask_b32_e32 v192, 0, v192, vcc
	v_cndmask_b32_e32 v193, 0, v193, vcc
	v_cndmask_b32_e32 v194, 0, v194, vcc
	v_cndmask_b32_e32 v195, 0, v195, vcc
	v_add_u32_e32 v28, -2, v175
	v_cmp_le_i32_e32 vcc, s31, v28
	s_nop 1
	v_cndmask_b32_e32 v196, 0, v196, vcc
	v_cndmask_b32_e32 v197, 0, v197, vcc
	v_cndmask_b32_e32 v198, 0, v198, vcc
	v_cndmask_b32_e32 v199, 0, v199, vcc
	v_add_u32_e32 v28, -1, v175
	v_cmp_le_i32_e32 vcc, s31, v28
	s_nop 1
	v_cndmask_b32_e32 v200, 0, v200, vcc
	v_cndmask_b32_e32 v201, 0, v201, vcc
	v_cndmask_b32_e32 v202, 0, v202, vcc
	v_cndmask_b32_e32 v203, 0, v203, vcc
	v_mov_b64_e32 v[224:225], v[0:1]
	v_mov_b64_e32 v[226:227], v[2:3]
	v_mov_b64_e32 v[228:229], v[4:5]
	v_mov_b64_e32 v[230:231], v[6:7]
	v_lshlrev_b32_e32 v28, 16, v192
	v_and_b32_e32 v29, 0xffff0000, v192
	v_pk_fma_f32 v[224:225], v[8:9], v[28:29], v[224:225]
	v_lshlrev_b32_e32 v28, 16, v193
	v_and_b32_e32 v29, 0xffff0000, v193
	v_pk_fma_f32 v[226:227], v[10:11], v[28:29], v[226:227]
	v_lshlrev_b32_e32 v28, 16, v194
	v_and_b32_e32 v29, 0xffff0000, v194
	v_pk_fma_f32 v[228:229], v[12:13], v[28:29], v[228:229]
	v_lshlrev_b32_e32 v28, 16, v195
	v_and_b32_e32 v29, 0xffff0000, v195
	v_pk_fma_f32 v[230:231], v[14:15], v[28:29], v[230:231]
	v_lshlrev_b32_e32 v28, 16, v196
	v_and_b32_e32 v29, 0xffff0000, v196
	v_pk_fma_f32 v[224:225], v[16:17], v[28:29], v[224:225]
	v_lshlrev_b32_e32 v28, 16, v197
	v_and_b32_e32 v29, 0xffff0000, v197
	v_pk_fma_f32 v[226:227], v[18:19], v[28:29], v[226:227]
	v_lshlrev_b32_e32 v28, 16, v198
	v_and_b32_e32 v29, 0xffff0000, v198
	v_pk_fma_f32 v[228:229], v[20:21], v[28:29], v[228:229]
	v_lshlrev_b32_e32 v28, 16, v199
	v_and_b32_e32 v29, 0xffff0000, v199
	v_pk_fma_f32 v[230:231], v[22:23], v[28:29], v[230:231]
	v_lshlrev_b32_e32 v28, 16, v200
	v_and_b32_e32 v29, 0xffff0000, v200
	v_pk_fma_f32 v[224:225], v[176:177], v[28:29], v[224:225]
	v_lshlrev_b32_e32 v28, 16, v201
	v_and_b32_e32 v29, 0xffff0000, v201
	v_pk_fma_f32 v[226:227], v[178:179], v[28:29], v[226:227]
	v_lshlrev_b32_e32 v28, 16, v202
	v_and_b32_e32 v29, 0xffff0000, v202
	v_pk_fma_f32 v[228:229], v[180:181], v[28:29], v[228:229]
	v_lshlrev_b32_e32 v28, 16, v203
	v_and_b32_e32 v29, 0xffff0000, v203
	v_pk_fma_f32 v[230:231], v[182:183], v[28:29], v[230:231]
	v_lshlrev_b32_e32 v28, 16, v204
	v_and_b32_e32 v29, 0xffff0000, v204
	v_pk_fma_f32 v[224:225], v[184:185], v[28:29], v[224:225]
	v_lshlrev_b32_e32 v28, 16, v205
	v_and_b32_e32 v29, 0xffff0000, v205
	v_pk_fma_f32 v[226:227], v[186:187], v[28:29], v[226:227]
	v_lshlrev_b32_e32 v28, 16, v206
	v_and_b32_e32 v29, 0xffff0000, v206
	v_pk_fma_f32 v[228:229], v[188:189], v[28:29], v[228:229]
	v_lshlrev_b32_e32 v28, 16, v207
	v_and_b32_e32 v29, 0xffff0000, v207
	v_pk_fma_f32 v[230:231], v[190:191], v[28:29], v[230:231]
	v_cvt_pk_bf16_f32 v224, v224, v225
	v_cvt_pk_bf16_f32 v225, v226, v227
	v_cvt_pk_bf16_f32 v226, v228, v229
	v_cvt_pk_bf16_f32 v227, v230, v231
	ds_write_b128 v234, v[224:227]
	s_waitcnt vmcnt(0)
	s_waitcnt lgkmcnt(0)
; DEVI unsigned pk2(float lo, float hi) { unsigned r; asm("v_cvt_pk_bf16_f32 %0, %1, %2" : "=v"(r) : "v"(lo), "v"(hi)); return r; }
; DEVI float bflo(unsigned w) { return __uint_as_float(w << 16); }
; DEVI float bfhi(unsigned w) { return __uint_as_float(w & 0xffff0000u); }
; DEVI void phase_m1(const Params& p, int l, unsigned char* smem) {
;     ...
;         for (int it = tid; it < 128 * 32; it += 512) {
;             const int t = it >> 5, c8 = (it & 31) * 8;
;             float a[8];
; #pragma unroll
;             for (int e = 0; e < 8; ++e) a[e] = p.in[15][l * 256 + c8 + e];
; #pragma unroll
;             for (int k = 0; k < 4; ++k) {
;                 const int tt = t - 3 + k;
;                 if (nloc * 128 + tt < 0) continue;
;                 const u32x4 x = *(const u32x4*)(proj + (size_t)(row0 + tt) * DIN + 1024 + c8);
;                 const f32x4 w0 = *(const f32x4*)(p.in[14] + ((size_t)l * 4 + k) * 256 + c8), w1 = *(const f32x4*)(p.in[14] + ((size_t)l * 4 + k) * 256 + c8 + 4);
;                 a[0] += w0[0] * bflo(x.x); a[1] += w0[1] * bfhi(x.x); a[2] += w0[2] * bflo(x.y); a[3] += w0[3] * bfhi(x.y);
;                 a[4] += w1[0] * bflo(x.z); a[5] += w1[1] * bfhi(x.z); a[6] += w1[2] * bflo(x.w); a[7] += w1[3] * bfhi(x.w);
;             }
;             u32x4 o; o.x = pk2(a[0], a[1]); o.y = pk2(a[2], a[3]); o.z = pk2(a[4], a[5]); o.w = pk2(a[6], a[7]);
;             *(u32x4*)(xc + t * 264 + c8) = o;
;         }
	v_mov_b64_e32 v[224:225], v[0:1]
	v_mov_b64_e32 v[226:227], v[2:3]
	v_mov_b64_e32 v[228:229], v[4:5]
	v_mov_b64_e32 v[230:231], v[6:7]
	v_lshlrev_b32_e32 v28, 16, v208
	v_and_b32_e32 v29, 0xffff0000, v208
	v_pk_fma_f32 v[224:225], v[8:9], v[28:29], v[224:225]
	v_lshlrev_b32_e32 v28, 16, v209
	v_and_b32_e32 v29, 0xffff0000, v209
	v_pk_fma_f32 v[226:227], v[10:11], v[28:29], v[226:227]
	v_lshlrev_b32_e32 v28, 16, v210
	v_and_b32_e32 v29, 0xffff0000, v210
	v_pk_fma_f32 v[228:229], v[12:13], v[28:29], v[228:229]
	v_lshlrev_b32_e32 v28, 16, v211
	v_and_b32_e32 v29, 0xffff0000, v211
	v_pk_fma_f32 v[230:231], v[14:15], v[28:29], v[230:231]
	v_lshlrev_b32_e32 v28, 16, v212
	v_and_b32_e32 v29, 0xffff0000, v212
	v_pk_fma_f32 v[224:225], v[16:17], v[28:29], v[224:225]
	v_lshlrev_b32_e32 v28, 16, v213
	v_and_b32_e32 v29, 0xffff0000, v213
	v_pk_fma_f32 v[226:227], v[18:19], v[28:29], v[226:227]
	v_lshlrev_b32_e32 v28, 16, v214
	v_and_b32_e32 v29, 0xffff0000, v214
	v_pk_fma_f32 v[228:229], v[20:21], v[28:29], v[228:229]
	v_lshlrev_b32_e32 v28, 16, v215
	v_and_b32_e32 v29, 0xffff0000, v215
	v_pk_fma_f32 v[230:231], v[22:23], v[28:29], v[230:231]
	v_lshlrev_b32_e32 v28, 16, v216
	v_and_b32_e32 v29, 0xffff0000, v216
	v_pk_fma_f32 v[224:225], v[176:177], v[28:29], v[224:225]
	v_lshlrev_b32_e32 v28, 16, v217
	v_and_b32_e32 v29, 0xffff0000, v217
	v_pk_fma_f32 v[226:227], v[178:179], v[28:29], v[226:227]
	v_lshlrev_b32_e32 v28, 16, v218
	v_and_b32_e32 v29, 0xffff0000, v218
	v_pk_fma_f32 v[228:229], v[180:181], v[28:29], v[228:229]
	v_lshlrev_b32_e32 v28, 16, v219
	v_and_b32_e32 v29, 0xffff0000, v219
	v_pk_fma_f32 v[230:231], v[182:183], v[28:29], v[230:231]
	v_lshlrev_b32_e32 v28, 16, v220
	v_and_b32_e32 v29, 0xffff0000, v220
	v_pk_fma_f32 v[224:225], v[184:185], v[28:29], v[224:225]
	v_lshlrev_b32_e32 v28, 16, v221
	v_and_b32_e32 v29, 0xffff0000, v221
	v_pk_fma_f32 v[226:227], v[186:187], v[28:29], v[226:227]
	v_lshlrev_b32_e32 v28, 16, v222
	v_and_b32_e32 v29, 0xffff0000, v222
	v_pk_fma_f32 v[228:229], v[188:189], v[28:29], v[228:229]
	v_lshlrev_b32_e32 v28, 16, v223
	v_and_b32_e32 v29, 0xffff0000, v223
	v_pk_fma_f32 v[230:231], v[190:191], v[28:29], v[230:231]
	v_cvt_pk_bf16_f32 v224, v224, v225
	v_cvt_pk_bf16_f32 v225, v226, v227
	v_cvt_pk_bf16_f32 v226, v228, v229
	v_cvt_pk_bf16_f32 v227, v230, v231
	ds_write_b128 v234, v[224:227] offset:8448
	global_load_dwordx4 v[192:195], v[24:25], off
	global_load_dwordx4 v[196:199], v[24:25], off offset:3072
	global_load_dwordx4 v[200:203], v[26:27], off
	global_load_dwordx4 v[204:207], v[26:27], off offset:3072
	v_lshl_add_u64 v[24:25], v[24:25], 0, s[98:99]
	v_lshl_add_u64 v[26:27], v[26:27], 0, s[98:99]
	global_load_dwordx4 v[208:211], v[24:25], off
	global_load_dwordx4 v[212:215], v[24:25], off offset:3072
	global_load_dwordx4 v[216:219], v[26:27], off
	global_load_dwordx4 v[220:223], v[26:27], off offset:3072
	v_lshl_add_u64 v[24:25], v[24:25], 0, s[98:99]
	v_lshl_add_u64 v[26:27], v[26:27], 0, s[98:99]
	s_waitcnt vmcnt(4)
	s_waitcnt lgkmcnt(0)
	v_mov_b64_e32 v[224:225], v[0:1]
	v_mov_b64_e32 v[226:227], v[2:3]
	v_mov_b64_e32 v[228:229], v[4:5]
	v_mov_b64_e32 v[230:231], v[6:7]
	v_lshlrev_b32_e32 v28, 16, v192
	v_and_b32_e32 v29, 0xffff0000, v192
	v_pk_fma_f32 v[224:225], v[8:9], v[28:29], v[224:225]
	v_lshlrev_b32_e32 v28, 16, v193
	v_and_b32_e32 v29, 0xffff0000, v193
	v_pk_fma_f32 v[226:227], v[10:11], v[28:29], v[226:227]
	v_lshlrev_b32_e32 v28, 16, v194
	v_and_b32_e32 v29, 0xffff0000, v194
	v_pk_fma_f32 v[228:229], v[12:13], v[28:29], v[228:229]
	v_lshlrev_b32_e32 v28, 16, v195
	v_and_b32_e32 v29, 0xffff0000, v195
	v_pk_fma_f32 v[230:231], v[14:15], v[28:29], v[230:231]
	v_lshlrev_b32_e32 v28, 16, v196
	v_and_b32_e32 v29, 0xffff0000, v196
	v_pk_fma_f32 v[224:225], v[16:17], v[28:29], v[224:225]
	v_lshlrev_b32_e32 v28, 16, v197
	v_and_b32_e32 v29, 0xffff0000, v197
	v_pk_fma_f32 v[226:227], v[18:19], v[28:29], v[226:227]
	v_lshlrev_b32_e32 v28, 16, v198
	v_and_b32_e32 v29, 0xffff0000, v198
	v_pk_fma_f32 v[228:229], v[20:21], v[28:29], v[228:229]
	v_lshlrev_b32_e32 v28, 16, v199
	v_and_b32_e32 v29, 0xffff0000, v199
	v_pk_fma_f32 v[230:231], v[22:23], v[28:29], v[230:231]
	v_lshlrev_b32_e32 v28, 16, v200
	v_and_b32_e32 v29, 0xffff0000, v200
	v_pk_fma_f32 v[224:225], v[176:177], v[28:29], v[224:225]
	v_lshlrev_b32_e32 v28, 16, v201
	v_and_b32_e32 v29, 0xffff0000, v201
	v_pk_fma_f32 v[226:227], v[178:179], v[28:29], v[226:227]
	v_lshlrev_b32_e32 v28, 16, v202
	v_and_b32_e32 v29, 0xffff0000, v202
	v_pk_fma_f32 v[228:229], v[180:181], v[28:29], v[228:229]
	v_lshlrev_b32_e32 v28, 16, v203
	v_and_b32_e32 v29, 0xffff0000, v203
	v_pk_fma_f32 v[230:231], v[182:183], v[28:29], v[230:231]
	v_lshlrev_b32_e32 v28, 16, v204
	v_and_b32_e32 v29, 0xffff0000, v204
	v_pk_fma_f32 v[224:225], v[184:185], v[28:29], v[224:225]
	v_lshlrev_b32_e32 v28, 16, v205
	v_and_b32_e32 v29, 0xffff0000, v205
	v_pk_fma_f32 v[226:227], v[186:187], v[28:29], v[226:227]
	v_lshlrev_b32_e32 v28, 16, v206
	v_and_b32_e32 v29, 0xffff0000, v206
	v_pk_fma_f32 v[228:229], v[188:189], v[28:29], v[228:229]
	v_lshlrev_b32_e32 v28, 16, v207
	v_and_b32_e32 v29, 0xffff0000, v207
	v_pk_fma_f32 v[230:231], v[190:191], v[28:29], v[230:231]
	v_cvt_pk_bf16_f32 v224, v224, v225
	v_cvt_pk_bf16_f32 v225, v226, v227
	v_cvt_pk_bf16_f32 v226, v228, v229
	v_cvt_pk_bf16_f32 v227, v230, v231
	ds_write_b128 v234, v[224:227] offset:16896
	s_waitcnt vmcnt(0)
	s_waitcnt lgkmcnt(0)
; DEVI unsigned pk2(float lo, float hi) { unsigned r; asm("v_cvt_pk_bf16_f32 %0, %1, %2" : "=v"(r) : "v"(lo), "v"(hi)); return r; }
; DEVI float bflo(unsigned w) { return __uint_as_float(w << 16); }
; DEVI float bfhi(unsigned w) { return __uint_as_float(w & 0xffff0000u); }
; DEVI void phase_m1(const Params& p, int l, unsigned char* smem) {
;     ...
;         for (int it = tid; it < 128 * 32; it += 512) {
;             const int t = it >> 5, c8 = (it & 31) * 8;
;             float a[8];
; #pragma unroll
;             for (int e = 0; e < 8; ++e) a[e] = p.in[15][l * 256 + c8 + e];
; #pragma unroll
;             for (int k = 0; k < 4; ++k) {
;                 const int tt = t - 3 + k;
;                 if (nloc * 128 + tt < 0) continue;
;                 const u32x4 x = *(const u32x4*)(proj + (size_t)(row0 + tt) * DIN + 1024 + c8);
;                 const f32x4 w0 = *(const f32x4*)(p.in[14] + ((size_t)l * 4 + k) * 256 + c8), w1 = *(const f32x4*)(p.in[14] + ((size_t)l * 4 + k) * 256 + c8 + 4);
;                 a[0] += w0[0] * bflo(x.x); a[1] += w0[1] * bfhi(x.x); a[2] += w0[2] * bflo(x.y); a[3] += w0[3] * bfhi(x.y);
;                 a[4] += w1[0] * bflo(x.z); a[5] += w1[1] * bfhi(x.z); a[6] += w1[2] * bflo(x.w); a[7] += w1[3] * bfhi(x.w);
;             }
;             u32x4 o; o.x = pk2(a[0], a[1]); o.y = pk2(a[2], a[3]); o.z = pk2(a[4], a[5]); o.w = pk2(a[6], a[7]);
;             *(u32x4*)(xc + t * 264 + c8) = o;
;         }
	v_mov_b64_e32 v[224:225], v[0:1]
	v_mov_b64_e32 v[226:227], v[2:3]
	v_mov_b64_e32 v[228:229], v[4:5]
	v_mov_b64_e32 v[230:231], v[6:7]
	v_lshlrev_b32_e32 v28, 16, v208
	v_and_b32_e32 v29, 0xffff0000, v208
	v_pk_fma_f32 v[224:225], v[8:9], v[28:29], v[224:225]
	v_lshlrev_b32_e32 v28, 16, v209
	v_and_b32_e32 v29, 0xffff0000, v209
	v_pk_fma_f32 v[226:227], v[10:11], v[28:29], v[226:227]
	v_lshlrev_b32_e32 v28, 16, v210
	v_and_b32_e32 v29, 0xffff0000, v210
	v_pk_fma_f32 v[228:229], v[12:13], v[28:29], v[228:229]
	v_lshlrev_b32_e32 v28, 16, v211
	v_and_b32_e32 v29, 0xffff0000, v211
	v_pk_fma_f32 v[230:231], v[14:15], v[28:29], v[230:231]
	v_lshlrev_b32_e32 v28, 16, v212
	v_and_b32_e32 v29, 0xffff0000, v212
	v_pk_fma_f32 v[224:225], v[16:17], v[28:29], v[224:225]
	v_lshlrev_b32_e32 v28, 16, v213
	v_and_b32_e32 v29, 0xffff0000, v213
	v_pk_fma_f32 v[226:227], v[18:19], v[28:29], v[226:227]
	v_lshlrev_b32_e32 v28, 16, v214
	v_and_b32_e32 v29, 0xffff0000, v214
	v_pk_fma_f32 v[228:229], v[20:21], v[28:29], v[228:229]
	v_lshlrev_b32_e32 v28, 16, v215
	v_and_b32_e32 v29, 0xffff0000, v215
	v_pk_fma_f32 v[230:231], v[22:23], v[28:29], v[230:231]
	v_lshlrev_b32_e32 v28, 16, v216
	v_and_b32_e32 v29, 0xffff0000, v216
	v_pk_fma_f32 v[224:225], v[176:177], v[28:29], v[224:225]
	v_lshlrev_b32_e32 v28, 16, v217
	v_and_b32_e32 v29, 0xffff0000, v217
	v_pk_fma_f32 v[226:227], v[178:179], v[28:29], v[226:227]
	v_lshlrev_b32_e32 v28, 16, v218
	v_and_b32_e32 v29, 0xffff0000, v218
	v_pk_fma_f32 v[228:229], v[180:181], v[28:29], v[228:229]
	v_lshlrev_b32_e32 v28, 16, v219
	v_and_b32_e32 v29, 0xffff0000, v219
	v_pk_fma_f32 v[230:231], v[182:183], v[28:29], v[230:231]
	v_lshlrev_b32_e32 v28, 16, v220
	v_and_b32_e32 v29, 0xffff0000, v220
	v_pk_fma_f32 v[224:225], v[184:185], v[28:29], v[224:225]
	v_lshlrev_b32_e32 v28, 16, v221
	v_and_b32_e32 v29, 0xffff0000, v221
	v_pk_fma_f32 v[226:227], v[186:187], v[28:29], v[226:227]
	v_lshlrev_b32_e32 v28, 16, v222
	v_and_b32_e32 v29, 0xffff0000, v222
	v_pk_fma_f32 v[228:229], v[188:189], v[28:29], v[228:229]
	v_lshlrev_b32_e32 v28, 16, v223
	v_and_b32_e32 v29, 0xffff0000, v223
	v_pk_fma_f32 v[230:231], v[190:191], v[28:29], v[230:231]
	v_cvt_pk_bf16_f32 v224, v224, v225
	v_cvt_pk_bf16_f32 v225, v226, v227
	v_cvt_pk_bf16_f32 v226, v228, v229
	v_cvt_pk_bf16_f32 v227, v230, v231
	ds_write_b128 v234, v[224:227] offset:25344
	global_load_dwordx4 v[192:195], v[24:25], off
	global_load_dwordx4 v[196:199], v[24:25], off offset:3072
	global_load_dwordx4 v[200:203], v[26:27], off
	global_load_dwordx4 v[204:207], v[26:27], off offset:3072
	v_lshl_add_u64 v[24:25], v[24:25], 0, s[98:99]
	v_lshl_add_u64 v[26:27], v[26:27], 0, s[98:99]
	global_load_dwordx4 v[208:211], v[24:25], off
	global_load_dwordx4 v[212:215], v[24:25], off offset:3072
	global_load_dwordx4 v[216:219], v[26:27], off
	global_load_dwordx4 v[220:223], v[26:27], off offset:3072
	v_lshl_add_u64 v[24:25], v[24:25], 0, s[98:99]
	v_lshl_add_u64 v[26:27], v[26:27], 0, s[98:99]
	s_waitcnt vmcnt(4)
	s_waitcnt lgkmcnt(0)
	v_mov_b64_e32 v[224:225], v[0:1]
	v_mov_b64_e32 v[226:227], v[2:3]
	v_mov_b64_e32 v[228:229], v[4:5]
	v_mov_b64_e32 v[230:231], v[6:7]
	v_lshlrev_b32_e32 v28, 16, v192
	v_and_b32_e32 v29, 0xffff0000, v192
	v_pk_fma_f32 v[224:225], v[8:9], v[28:29], v[224:225]
	v_lshlrev_b32_e32 v28, 16, v193
	v_and_b32_e32 v29, 0xffff0000, v193
	v_pk_fma_f32 v[226:227], v[10:11], v[28:29], v[226:227]
	v_lshlrev_b32_e32 v28, 16, v194
	v_and_b32_e32 v29, 0xffff0000, v194
	v_pk_fma_f32 v[228:229], v[12:13], v[28:29], v[228:229]
	v_lshlrev_b32_e32 v28, 16, v195
	v_and_b32_e32 v29, 0xffff0000, v195
	v_pk_fma_f32 v[230:231], v[14:15], v[28:29], v[230:231]
	v_lshlrev_b32_e32 v28, 16, v196
	v_and_b32_e32 v29, 0xffff0000, v196
	v_pk_fma_f32 v[224:225], v[16:17], v[28:29], v[224:225]
	v_lshlrev_b32_e32 v28, 16, v197
	v_and_b32_e32 v29, 0xffff0000, v197
	v_pk_fma_f32 v[226:227], v[18:19], v[28:29], v[226:227]
	v_lshlrev_b32_e32 v28, 16, v198
	v_and_b32_e32 v29, 0xffff0000, v198
	v_pk_fma_f32 v[228:229], v[20:21], v[28:29], v[228:229]
	v_lshlrev_b32_e32 v28, 16, v199
	v_and_b32_e32 v29, 0xffff0000, v199
	v_pk_fma_f32 v[230:231], v[22:23], v[28:29], v[230:231]
	v_lshlrev_b32_e32 v28, 16, v200
	v_and_b32_e32 v29, 0xffff0000, v200
	v_pk_fma_f32 v[224:225], v[176:177], v[28:29], v[224:225]
	v_lshlrev_b32_e32 v28, 16, v201
	v_and_b32_e32 v29, 0xffff0000, v201
	v_pk_fma_f32 v[226:227], v[178:179], v[28:29], v[226:227]
	v_lshlrev_b32_e32 v28, 16, v202
	v_and_b32_e32 v29, 0xffff0000, v202
	v_pk_fma_f32 v[228:229], v[180:181], v[28:29], v[228:229]
	v_lshlrev_b32_e32 v28, 16, v203
	v_and_b32_e32 v29, 0xffff0000, v203
	v_pk_fma_f32 v[230:231], v[182:183], v[28:29], v[230:231]
	v_lshlrev_b32_e32 v28, 16, v204
	v_and_b32_e32 v29, 0xffff0000, v204
	v_pk_fma_f32 v[224:225], v[184:185], v[28:29], v[224:225]
	v_lshlrev_b32_e32 v28, 16, v205
	v_and_b32_e32 v29, 0xffff0000, v205
	v_pk_fma_f32 v[226:227], v[186:187], v[28:29], v[226:227]
	v_lshlrev_b32_e32 v28, 16, v206
	v_and_b32_e32 v29, 0xffff0000, v206
	v_pk_fma_f32 v[228:229], v[188:189], v[28:29], v[228:229]
	v_lshlrev_b32_e32 v28, 16, v207
	v_and_b32_e32 v29, 0xffff0000, v207
	v_pk_fma_f32 v[230:231], v[190:191], v[28:29], v[230:231]
	v_cvt_pk_bf16_f32 v224, v224, v225
	v_cvt_pk_bf16_f32 v225, v226, v227
	v_cvt_pk_bf16_f32 v226, v228, v229
	v_cvt_pk_bf16_f32 v227, v230, v231
	ds_write_b128 v234, v[224:227] offset:33792
	s_waitcnt vmcnt(0)
	s_waitcnt lgkmcnt(0)
; DEVI unsigned pk2(float lo, float hi) { unsigned r; asm("v_cvt_pk_bf16_f32 %0, %1, %2" : "=v"(r) : "v"(lo), "v"(hi)); return r; }
; DEVI float bflo(unsigned w) { return __uint_as_float(w << 16); }
; DEVI float bfhi(unsigned w) { return __uint_as_float(w & 0xffff0000u); }
; DEVI void phase_m1(const Params& p, int l, unsigned char* smem) {
;     ...
;         for (int it = tid; it < 128 * 32; it += 512) {
;             const int t = it >> 5, c8 = (it & 31) * 8;
;             float a[8];
; #pragma unroll
;             for (int e = 0; e < 8; ++e) a[e] = p.in[15][l * 256 + c8 + e];
; #pragma unroll
;             for (int k = 0; k < 4; ++k) {
;                 const int tt = t - 3 + k;
;                 if (nloc * 128 + tt < 0) continue;
;                 const u32x4 x = *(const u32x4*)(proj + (size_t)(row0 + tt) * DIN + 1024 + c8);
;                 const f32x4 w0 = *(const f32x4*)(p.in[14] + ((size_t)l * 4 + k) * 256 + c8), w1 = *(const f32x4*)(p.in[14] + ((size_t)l * 4 + k) * 256 + c8 + 4);
;                 a[0] += w0[0] * bflo(x.x); a[1] += w0[1] * bfhi(x.x); a[2] += w0[2] * bflo(x.y); a[3] += w0[3] * bfhi(x.y);
;                 a[4] += w1[0] * bflo(x.z); a[5] += w1[1] * bfhi(x.z); a[6] += w1[2] * bflo(x.w); a[7] += w1[3] * bfhi(x.w);
;             }
;             u32x4 o; o.x = pk2(a[0], a[1]); o.y = pk2(a[2], a[3]); o.z = pk2(a[4], a[5]); o.w = pk2(a[6], a[7]);
;             *(u32x4*)(xc + t * 264 + c8) = o;
;         }
	v_mov_b64_e32 v[224:225], v[0:1]
	v_mov_b64_e32 v[226:227], v[2:3]
	v_mov_b64_e32 v[228:229], v[4:5]
	v_mov_b64_e32 v[230:231], v[6:7]
	v_lshlrev_b32_e32 v28, 16, v208
	v_and_b32_e32 v29, 0xffff0000, v208
	v_pk_fma_f32 v[224:225], v[8:9], v[28:29], v[224:225]
	v_lshlrev_b32_e32 v28, 16, v209
	v_and_b32_e32 v29, 0xffff0000, v209
	v_pk_fma_f32 v[226:227], v[10:11], v[28:29], v[226:227]
	v_lshlrev_b32_e32 v28, 16, v210
	v_and_b32_e32 v29, 0xffff0000, v210
	v_pk_fma_f32 v[228:229], v[12:13], v[28:29], v[228:229]
	v_lshlrev_b32_e32 v28, 16, v211
	v_and_b32_e32 v29, 0xffff0000, v211
	v_pk_fma_f32 v[230:231], v[14:15], v[28:29], v[230:231]
	v_lshlrev_b32_e32 v28, 16, v212
	v_and_b32_e32 v29, 0xffff0000, v212
	v_pk_fma_f32 v[224:225], v[16:17], v[28:29], v[224:225]
	v_lshlrev_b32_e32 v28, 16, v213
	v_and_b32_e32 v29, 0xffff0000, v213
	v_pk_fma_f32 v[226:227], v[18:19], v[28:29], v[226:227]
	v_lshlrev_b32_e32 v28, 16, v214
	v_and_b32_e32 v29, 0xffff0000, v214
	v_pk_fma_f32 v[228:229], v[20:21], v[28:29], v[228:229]
	v_lshlrev_b32_e32 v28, 16, v215
	v_and_b32_e32 v29, 0xffff0000, v215
	v_pk_fma_f32 v[230:231], v[22:23], v[28:29], v[230:231]
	v_lshlrev_b32_e32 v28, 16, v216
	v_and_b32_e32 v29, 0xffff0000, v216
	v_pk_fma_f32 v[224:225], v[176:177], v[28:29], v[224:225]
	v_lshlrev_b32_e32 v28, 16, v217
	v_and_b32_e32 v29, 0xffff0000, v217
	v_pk_fma_f32 v[226:227], v[178:179], v[28:29], v[226:227]
	v_lshlrev_b32_e32 v28, 16, v218
	v_and_b32_e32 v29, 0xffff0000, v218
	v_pk_fma_f32 v[228:229], v[180:181], v[28:29], v[228:229]
	v_lshlrev_b32_e32 v28, 16, v219
	v_and_b32_e32 v29, 0xffff0000, v219
	v_pk_fma_f32 v[230:231], v[182:183], v[28:29], v[230:231]
	v_lshlrev_b32_e32 v28, 16, v220
	v_and_b32_e32 v29, 0xffff0000, v220
	v_pk_fma_f32 v[224:225], v[184:185], v[28:29], v[224:225]
	v_lshlrev_b32_e32 v28, 16, v221
	v_and_b32_e32 v29, 0xffff0000, v221
	v_pk_fma_f32 v[226:227], v[186:187], v[28:29], v[226:227]
	v_lshlrev_b32_e32 v28, 16, v222
	v_and_b32_e32 v29, 0xffff0000, v222
	v_pk_fma_f32 v[228:229], v[188:189], v[28:29], v[228:229]
	v_lshlrev_b32_e32 v28, 16, v223
	v_and_b32_e32 v29, 0xffff0000, v223
	v_pk_fma_f32 v[230:231], v[190:191], v[28:29], v[230:231]
	v_cvt_pk_bf16_f32 v224, v224, v225
	v_cvt_pk_bf16_f32 v225, v226, v227
	v_cvt_pk_bf16_f32 v226, v228, v229
	v_cvt_pk_bf16_f32 v227, v230, v231
	ds_write_b128 v234, v[224:227] offset:42240
	global_load_dwordx4 v[192:195], v[24:25], off
	global_load_dwordx4 v[196:199], v[24:25], off offset:3072
	global_load_dwordx4 v[200:203], v[26:27], off
	global_load_dwordx4 v[204:207], v[26:27], off offset:3072
	v_lshl_add_u64 v[24:25], v[24:25], 0, s[98:99]
	v_lshl_add_u64 v[26:27], v[26:27], 0, s[98:99]
	global_load_dwordx4 v[208:211], v[24:25], off
	global_load_dwordx4 v[212:215], v[24:25], off offset:3072
	global_load_dwordx4 v[216:219], v[26:27], off
	global_load_dwordx4 v[220:223], v[26:27], off offset:3072
	v_lshl_add_u64 v[24:25], v[24:25], 0, s[98:99]
	v_lshl_add_u64 v[26:27], v[26:27], 0, s[98:99]
	s_waitcnt vmcnt(4)
	s_waitcnt lgkmcnt(0)
; DEVI unsigned pk2(float lo, float hi) { unsigned r; asm("v_cvt_pk_bf16_f32 %0, %1, %2" : "=v"(r) : "v"(lo), "v"(hi)); return r; }
; DEVI float bflo(unsigned w) { return __uint_as_float(w << 16); }
; DEVI float bfhi(unsigned w) { return __uint_as_float(w & 0xffff0000u); }
; DEVI void phase_m1(const Params& p, int l, unsigned char* smem) {
;     ...
;         for (int it = tid; it < 128 * 32; it += 512) {
;             const int t = it >> 5, c8 = (it & 31) * 8;
;             float a[8];
; #pragma unroll
;             for (int e = 0; e < 8; ++e) a[e] = p.in[15][l * 256 + c8 + e];
; #pragma unroll
;             for (int k = 0; k < 4; ++k) {
;                 const int tt = t - 3 + k;
;                 if (nloc * 128 + tt < 0) continue;
;                 const u32x4 x = *(const u32x4*)(proj + (size_t)(row0 + tt) * DIN + 1024 + c8);
;                 const f32x4 w0 = *(const f32x4*)(p.in[14] + ((size_t)l * 4 + k) * 256 + c8), w1 = *(const f32x4*)(p.in[14] + ((size_t)l * 4 + k) * 256 + c8 + 4);
;                 a[0] += w0[0] * bflo(x.x); a[1] += w0[1] * bfhi(x.x); a[2] += w0[2] * bflo(x.y); a[3] += w0[3] * bfhi(x.y);
;                 a[4] += w1[0] * bflo(x.z); a[5] += w1[1] * bfhi(x.z); a[6] += w1[2] * bflo(x.w); a[7] += w1[3] * bfhi(x.w);
;             }
;             u32x4 o; o.x = pk2(a[0], a[1]); o.y = pk2(a[2], a[3]); o.z = pk2(a[4], a[5]); o.w = pk2(a[6], a[7]);
;             *(u32x4*)(xc + t * 264 + c8) = o;
;         }
	v_mov_b64_e32 v[224:225], v[0:1]
	v_mov_b64_e32 v[226:227], v[2:3]
	v_mov_b64_e32 v[228:229], v[4:5]
	v_mov_b64_e32 v[230:231], v[6:7]
	v_lshlrev_b32_e32 v28, 16, v192
	v_and_b32_e32 v29, 0xffff0000, v192
	v_pk_fma_f32 v[224:225], v[8:9], v[28:29], v[224:225]
	v_lshlrev_b32_e32 v28, 16, v193
	v_and_b32_e32 v29, 0xffff0000, v193
	v_pk_fma_f32 v[226:227], v[10:11], v[28:29], v[226:227]
	v_lshlrev_b32_e32 v28, 16, v194
	v_and_b32_e32 v29, 0xffff0000, v194
	v_pk_fma_f32 v[228:229], v[12:13], v[28:29], v[228:229]
	v_lshlrev_b32_e32 v28, 16, v195
	v_and_b32_e32 v29, 0xffff0000, v195
	v_pk_fma_f32 v[230:231], v[14:15], v[28:29], v[230:231]
	v_lshlrev_b32_e32 v28, 16, v196
	v_and_b32_e32 v29, 0xffff0000, v196
	v_pk_fma_f32 v[224:225], v[16:17], v[28:29], v[224:225]
	v_lshlrev_b32_e32 v28, 16, v197
	v_and_b32_e32 v29, 0xffff0000, v197
	v_pk_fma_f32 v[226:227], v[18:19], v[28:29], v[226:227]
	v_lshlrev_b32_e32 v28, 16, v198
	v_and_b32_e32 v29, 0xffff0000, v198
	v_pk_fma_f32 v[228:229], v[20:21], v[28:29], v[228:229]
	v_lshlrev_b32_e32 v28, 16, v199
	v_and_b32_e32 v29, 0xffff0000, v199
	v_pk_fma_f32 v[230:231], v[22:23], v[28:29], v[230:231]
	v_lshlrev_b32_e32 v28, 16, v200
	v_and_b32_e32 v29, 0xffff0000, v200
	v_pk_fma_f32 v[224:225], v[176:177], v[28:29], v[224:225]
	v_lshlrev_b32_e32 v28, 16, v201
	v_and_b32_e32 v29, 0xffff0000, v201
	v_pk_fma_f32 v[226:227], v[178:179], v[28:29], v[226:227]
	v_lshlrev_b32_e32 v28, 16, v202
	v_and_b32_e32 v29, 0xffff0000, v202
	v_pk_fma_f32 v[228:229], v[180:181], v[28:29], v[228:229]
	v_lshlrev_b32_e32 v28, 16, v203
	v_and_b32_e32 v29, 0xffff0000, v203
	v_pk_fma_f32 v[230:231], v[182:183], v[28:29], v[230:231]
	v_lshlrev_b32_e32 v28, 16, v204
	v_and_b32_e32 v29, 0xffff0000, v204
	v_pk_fma_f32 v[224:225], v[184:185], v[28:29], v[224:225]
	v_lshlrev_b32_e32 v28, 16, v205
	v_and_b32_e32 v29, 0xffff0000, v205
	v_pk_fma_f32 v[226:227], v[186:187], v[28:29], v[226:227]
	v_lshlrev_b32_e32 v28, 16, v206
	v_and_b32_e32 v29, 0xffff0000, v206
	v_pk_fma_f32 v[228:229], v[188:189], v[28:29], v[228:229]
	v_lshlrev_b32_e32 v28, 16, v207
	v_and_b32_e32 v29, 0xffff0000, v207
	v_pk_fma_f32 v[230:231], v[190:191], v[28:29], v[230:231]
	v_cvt_pk_bf16_f32 v224, v224, v225
	v_cvt_pk_bf16_f32 v225, v226, v227
	v_cvt_pk_bf16_f32 v226, v228, v229
	v_cvt_pk_bf16_f32 v227, v230, v231
	ds_write_b128 v234, v[224:227] offset:50688
	s_waitcnt vmcnt(0)
	s_waitcnt lgkmcnt(0)
	v_mov_b64_e32 v[224:225], v[0:1]
	v_mov_b64_e32 v[226:227], v[2:3]
	v_mov_b64_e32 v[228:229], v[4:5]
	v_mov_b64_e32 v[230:231], v[6:7]
	v_lshlrev_b32_e32 v28, 16, v208
	v_and_b32_e32 v29, 0xffff0000, v208
	v_pk_fma_f32 v[224:225], v[8:9], v[28:29], v[224:225]
	v_lshlrev_b32_e32 v28, 16, v209
	v_and_b32_e32 v29, 0xffff0000, v209
	v_pk_fma_f32 v[226:227], v[10:11], v[28:29], v[226:227]
	v_lshlrev_b32_e32 v28, 16, v210
	v_and_b32_e32 v29, 0xffff0000, v210
	v_pk_fma_f32 v[228:229], v[12:13], v[28:29], v[228:229]
	v_lshlrev_b32_e32 v28, 16, v211
	v_and_b32_e32 v29, 0xffff0000, v211
	v_pk_fma_f32 v[230:231], v[14:15], v[28:29], v[230:231]
	v_lshlrev_b32_e32 v28, 16, v212
	v_and_b32_e32 v29, 0xffff0000, v212
	v_pk_fma_f32 v[224:225], v[16:17], v[28:29], v[224:225]
	v_lshlrev_b32_e32 v28, 16, v213
	v_and_b32_e32 v29, 0xffff0000, v213
	v_pk_fma_f32 v[226:227], v[18:19], v[28:29], v[226:227]
	v_lshlrev_b32_e32 v28, 16, v214
	v_and_b32_e32 v29, 0xffff0000, v214
	v_pk_fma_f32 v[228:229], v[20:21], v[28:29], v[228:229]
	v_lshlrev_b32_e32 v28, 16, v215
	v_and_b32_e32 v29, 0xffff0000, v215
	v_pk_fma_f32 v[230:231], v[22:23], v[28:29], v[230:231]
	v_lshlrev_b32_e32 v28, 16, v216
	v_and_b32_e32 v29, 0xffff0000, v216
	v_pk_fma_f32 v[224:225], v[176:177], v[28:29], v[224:225]
	v_lshlrev_b32_e32 v28, 16, v217
	v_and_b32_e32 v29, 0xffff0000, v217
	v_pk_fma_f32 v[226:227], v[178:179], v[28:29], v[226:227]
	v_lshlrev_b32_e32 v28, 16, v218
	v_and_b32_e32 v29, 0xffff0000, v218
	v_pk_fma_f32 v[228:229], v[180:181], v[28:29], v[228:229]
	v_lshlrev_b32_e32 v28, 16, v219
	v_and_b32_e32 v29, 0xffff0000, v219
	v_pk_fma_f32 v[230:231], v[182:183], v[28:29], v[230:231]
	v_lshlrev_b32_e32 v28, 16, v220
	v_and_b32_e32 v29, 0xffff0000, v220
	v_pk_fma_f32 v[224:225], v[184:185], v[28:29], v[224:225]
	v_lshlrev_b32_e32 v28, 16, v221
	v_and_b32_e32 v29, 0xffff0000, v221
	v_pk_fma_f32 v[226:227], v[186:187], v[28:29], v[226:227]
	v_lshlrev_b32_e32 v28, 16, v222
	v_and_b32_e32 v29, 0xffff0000, v222
	v_pk_fma_f32 v[228:229], v[188:189], v[28:29], v[228:229]
	v_lshlrev_b32_e32 v28, 16, v223
	v_and_b32_e32 v29, 0xffff0000, v223
	v_pk_fma_f32 v[230:231], v[190:191], v[28:29], v[230:231]
	v_cvt_pk_bf16_f32 v224, v224, v225
	v_cvt_pk_bf16_f32 v225, v226, v227
	v_cvt_pk_bf16_f32 v226, v228, v229
	v_cvt_pk_bf16_f32 v227, v230, v231
	ds_write_b128 v234, v[224:227] offset:59136
